# GEMM MODE-1 epilogue (wout, wo): unrolled, Hres loads of next iteration issued before stores of current one
# baseline (speedup 1.0000x reference)
; DI unsigned pack2(float a, float b) { const f32x2 v = {a, b}; return __builtin_bit_cast(unsigned, __builtin_convertvector(v, bf16v2)); }
; template <int SWAP, int MODE>
; DI void epilogue8(const f32x4 (&acc)[2][2][4][2], char* lds, u16* __restrict__ dst, size_t ld, const u16* __restrict__ Hres) {
;     ...
; #pragma unroll 4
;   for (int i = 0; i < 16; ++i) {
;     const int q = tid + 512 * i, r = q >> 5, c8 = (q & 31) * 8;
;     uint4 v = *(const uint4*)(Ct + r * CT_LD + c8);
;     const size_t o = (size_t)r * ld + c8;
;     if (MODE == 1) {
;       const uint4 hv = *(const uint4*)(Hres + o);
;       float y[8], hx[8]; unpack8(v, y); unpack8(hv, hx);
;       v.x = pack2(ALPHA * hx[0] + y[0], ALPHA * hx[1] + y[1]); v.y = pack2(ALPHA * hx[2] + y[2], ALPHA * hx[3] + y[3]);
;       v.z = pack2(ALPHA * hx[4] + y[4], ALPHA * hx[5] + y[5]); v.w = pack2(ALPHA * hx[6] + y[6], ALPHA * hx[7] + y[7]);
;     }
;     *(uint4*)(dst + o) = v;
.LBB0_702:
	v_add_u32_e32 v70, s16, v128
	v_ashrrev_i32_e32 v72, 5, v70
	v_add_u32_e32 v71, 0x200, v70
	v_ashrrev_i32_e32 v74, 5, v71
	v_add_u32_e32 v71, 0x400, v70
	v_ashrrev_i32_e32 v76, 5, v71
	v_add_u32_e32 v71, 0x600, v70
	v_ashrrev_i32_e32 v78, 5, v71
	v_ashrrev_i32_e32 v73, 31, v72
	v_lshlrev_b64 v[72:73], 11, v[72:73]
	v_or_b32_e32 v72, v72, v1
	v_lshl_add_u64 v[72:73], s[30:31], 0, v[72:73]
	v_ashrrev_i32_e32 v75, 31, v74
	v_lshlrev_b64 v[74:75], 11, v[74:75]
	v_or_b32_e32 v74, v74, v1
	v_lshl_add_u64 v[74:75], s[30:31], 0, v[74:75]
	v_ashrrev_i32_e32 v77, 31, v76
	v_lshlrev_b64 v[76:77], 11, v[76:77]
	v_or_b32_e32 v76, v76, v1
	v_lshl_add_u64 v[76:77], s[30:31], 0, v[76:77]
	v_ashrrev_i32_e32 v79, 31, v78
	v_lshlrev_b64 v[78:79], 11, v[78:79]
	v_or_b32_e32 v78, v78, v1
	v_lshl_add_u64 v[78:79], s[30:31], 0, v[78:79]
	global_load_dwordx4 v[94:97], v[72:73], off
	global_load_dwordx4 v[98:101], v[74:75], off
	global_load_dwordx4 v[102:105], v[76:77], off
	global_load_dwordx4 v[106:109], v[78:79], off
	v_add_u32_e32 v2, s16, v128
	v_ashrrev_i32_e32 v6, 5, v2
	v_add_u32_e32 v4, 0x200, v2
	v_add_u32_e32 v5, 0x400, v2
	v_add_u32_e32 v8, 0x600, v2
	v_ashrrev_i32_e32 v7, 31, v6
	v_ashrrev_i32_e32 v10, 5, v4
	v_ashrrev_i32_e32 v14, 5, v5
	v_ashrrev_i32_e32 v18, 5, v8
	v_lshlrev_b64 v[20:21], 11, v[6:7]
	v_ashrrev_i32_e32 v11, 31, v10
	v_ashrrev_i32_e32 v15, 31, v14
	v_ashrrev_i32_e32 v19, 31, v18
	v_or_b32_e32 v20, v20, v1
	v_mad_u64_u32 v[16:17], s[22:23], v18, s40, v[0:1]
	v_lshlrev_b64 v[22:23], 11, v[10:11]
	v_lshlrev_b64 v[24:25], 11, v[14:15]
	v_lshlrev_b64 v[26:27], 11, v[18:19]
	v_lshl_add_u64 v[18:19], s[30:31], 0, v[20:21]
	v_lshl_add_u64 v[34:35], s[26:27], 0, v[20:21]
	v_or_b32_e32 v22, v22, v1
	v_or_b32_e32 v24, v24, v1
	v_or_b32_e32 v26, v26, v1
	v_mad_u64_u32 v[2:3], s[22:23], v6, s40, v[0:1]
	v_mad_u64_u32 v[6:7], s[22:23], v10, s40, v[0:1]
	v_mad_u64_u32 v[12:13], s[22:23], v14, s40, v[0:1]
	v_lshl_add_u64 v[28:29], s[30:31], 0, v[22:23]
	v_lshl_add_u64 v[30:31], s[30:31], 0, v[24:25]
	v_lshl_add_u64 v[32:33], s[30:31], 0, v[26:27]
	ds_read_b128 v[2:5], v2
	ds_read_b128 v[6:9], v6
	ds_read_b128 v[10:13], v12
	ds_read_b128 v[14:17], v16
	v_lshl_add_u64 v[36:37], s[26:27], 0, v[22:23]
	v_lshl_add_u64 v[38:39], s[26:27], 0, v[24:25]
	v_lshl_add_u64 v[40:41], s[26:27], 0, v[26:27]
	s_nop 0
	s_nop 0
	s_waitcnt lgkmcnt(3)
	v_lshlrev_b32_e32 v42, 16, v2
	v_and_b32_e32 v43, 0xffff0000, v2
	v_lshlrev_b32_e32 v2, 16, v3
	v_and_b32_e32 v3, 0xffff0000, v3
	v_lshlrev_b32_e32 v44, 16, v4
	v_and_b32_e32 v45, 0xffff0000, v4
	v_lshlrev_b32_e32 v4, 16, v5
	v_and_b32_e32 v5, 0xffff0000, v5
	s_waitcnt lgkmcnt(2)
	v_lshlrev_b32_e32 v46, 16, v6
	v_and_b32_e32 v47, 0xffff0000, v6
	v_lshlrev_b32_e32 v6, 16, v7
	v_and_b32_e32 v7, 0xffff0000, v7
	v_lshlrev_b32_e32 v48, 16, v8
	v_and_b32_e32 v49, 0xffff0000, v8
	v_lshlrev_b32_e32 v8, 16, v9
	v_and_b32_e32 v9, 0xffff0000, v9
	s_addk_i32 s16, 0x800
	s_waitcnt lgkmcnt(1)
	v_lshlrev_b32_e32 v50, 16, v10
	v_and_b32_e32 v51, 0xffff0000, v10
	v_lshlrev_b32_e32 v10, 16, v11
	v_and_b32_e32 v11, 0xffff0000, v11
	v_lshlrev_b32_e32 v52, 16, v12
	v_and_b32_e32 v53, 0xffff0000, v12
	v_lshlrev_b32_e32 v12, 16, v13
	v_and_b32_e32 v13, 0xffff0000, v13
	s_waitcnt lgkmcnt(0)
	v_lshlrev_b32_e32 v54, 16, v14
	v_and_b32_e32 v55, 0xffff0000, v14
	v_lshlrev_b32_e32 v14, 16, v15
	v_and_b32_e32 v15, 0xffff0000, v15
	v_lshlrev_b32_e32 v56, 16, v16
	v_and_b32_e32 v57, 0xffff0000, v16
	v_lshlrev_b32_e32 v16, 16, v17
	v_and_b32_e32 v17, 0xffff0000, v17
	s_waitcnt vmcnt(3)
	v_mov_b32_e32 v18, v94
	v_mov_b32_e32 v19, v95
	v_mov_b32_e32 v20, v96
	v_mov_b32_e32 v21, v97
	v_lshlrev_b32_e32 v58, 16, v18
	v_and_b32_e32 v59, 0xffff0000, v18
	v_lshlrev_b32_e32 v18, 16, v19
	v_and_b32_e32 v19, 0xffff0000, v19
	v_lshlrev_b32_e32 v60, 16, v20
	v_and_b32_e32 v61, 0xffff0000, v20
	v_lshlrev_b32_e32 v20, 16, v21
	v_and_b32_e32 v21, 0xffff0000, v21
	v_pk_fma_f32 v[42:43], v[58:59], s[18:19], v[42:43] op_sel_hi:[1,0,1]
	v_pk_fma_f32 v[18:19], v[18:19], s[18:19], v[2:3] op_sel_hi:[1,0,1]
	v_pk_fma_f32 v[44:45], v[60:61], s[18:19], v[44:45] op_sel_hi:[1,0,1]
	v_pk_fma_f32 v[20:21], v[20:21], s[18:19], v[4:5] op_sel_hi:[1,0,1]
	v_cvt_pk_bf16_f32 v2, v42, v43
	v_cvt_pk_bf16_f32 v3, v18, v19
	v_cvt_pk_bf16_f32 v4, v44, v45
	s_waitcnt vmcnt(2)
	v_mov_b32_e32 v22, v98
	v_mov_b32_e32 v23, v99
	v_mov_b32_e32 v24, v100
	v_mov_b32_e32 v25, v101
	v_lshlrev_b32_e32 v58, 16, v22
	v_and_b32_e32 v59, 0xffff0000, v22
	v_lshlrev_b32_e32 v22, 16, v23
	v_and_b32_e32 v23, 0xffff0000, v23
	v_lshlrev_b32_e32 v60, 16, v24
	v_and_b32_e32 v61, 0xffff0000, v24
	v_lshlrev_b32_e32 v24, 16, v25
	v_and_b32_e32 v25, 0xffff0000, v25
	s_waitcnt vmcnt(1)
	v_mov_b32_e32 v26, v102
	v_mov_b32_e32 v27, v103
	v_mov_b32_e32 v28, v104
	v_mov_b32_e32 v29, v105
	v_lshlrev_b32_e32 v62, 16, v26
	v_and_b32_e32 v63, 0xffff0000, v26
	v_lshlrev_b32_e32 v26, 16, v27
	v_and_b32_e32 v27, 0xffff0000, v27
	v_lshlrev_b32_e32 v64, 16, v28
	v_and_b32_e32 v65, 0xffff0000, v28
	v_lshlrev_b32_e32 v28, 16, v29
	v_and_b32_e32 v29, 0xffff0000, v29
	s_waitcnt vmcnt(0)
; DI unsigned pack2(float a, float b) { const f32x2 v = {a, b}; return __builtin_bit_cast(unsigned, __builtin_convertvector(v, bf16v2)); }
; template <int SWAP, int MODE>
; DI void epilogue8(const f32x4 (&acc)[2][2][4][2], char* lds, u16* __restrict__ dst, size_t ld, const u16* __restrict__ Hres) {
;     ...
; #pragma unroll 4
;   for (int i = 0; i < 16; ++i) {
;     const int q = tid + 512 * i, r = q >> 5, c8 = (q & 31) * 8;
;     uint4 v = *(const uint4*)(Ct + r * CT_LD + c8);
;     const size_t o = (size_t)r * ld + c8;
;     if (MODE == 1) {
;       const uint4 hv = *(const uint4*)(Hres + o);
;       float y[8], hx[8]; unpack8(v, y); unpack8(hv, hx);
;       v.x = pack2(ALPHA * hx[0] + y[0], ALPHA * hx[1] + y[1]); v.y = pack2(ALPHA * hx[2] + y[2], ALPHA * hx[3] + y[3]);
;       v.z = pack2(ALPHA * hx[4] + y[4], ALPHA * hx[5] + y[5]); v.w = pack2(ALPHA * hx[6] + y[6], ALPHA * hx[7] + y[7]);
;     }
;     *(uint4*)(dst + o) = v;
	v_mov_b32_e32 v30, v106
	v_mov_b32_e32 v31, v107
	v_mov_b32_e32 v32, v108
	v_mov_b32_e32 v33, v109
	v_lshlrev_b32_e32 v66, 16, v30
	v_and_b32_e32 v67, 0xffff0000, v30
	v_lshlrev_b32_e32 v30, 16, v31
	v_and_b32_e32 v31, 0xffff0000, v31
	v_lshlrev_b32_e32 v68, 16, v32
	v_and_b32_e32 v69, 0xffff0000, v32
	v_lshlrev_b32_e32 v32, 16, v33
	v_and_b32_e32 v33, 0xffff0000, v33
	v_cvt_pk_bf16_f32 v5, v20, v21
	v_pk_fma_f32 v[18:19], v[58:59], s[18:19], v[46:47] op_sel_hi:[1,0,1]
	v_pk_fma_f32 v[6:7], v[22:23], s[18:19], v[6:7] op_sel_hi:[1,0,1]
	v_pk_fma_f32 v[20:21], v[60:61], s[18:19], v[48:49] op_sel_hi:[1,0,1]
	v_pk_fma_f32 v[8:9], v[24:25], s[18:19], v[8:9] op_sel_hi:[1,0,1]
	v_pk_fma_f32 v[22:23], v[62:63], s[18:19], v[50:51] op_sel_hi:[1,0,1]
	v_pk_fma_f32 v[10:11], v[26:27], s[18:19], v[10:11] op_sel_hi:[1,0,1]
	v_pk_fma_f32 v[24:25], v[64:65], s[18:19], v[52:53] op_sel_hi:[1,0,1]
	v_pk_fma_f32 v[12:13], v[28:29], s[18:19], v[12:13] op_sel_hi:[1,0,1]
	v_pk_fma_f32 v[26:27], v[66:67], s[18:19], v[54:55] op_sel_hi:[1,0,1]
	v_pk_fma_f32 v[14:15], v[30:31], s[18:19], v[14:15] op_sel_hi:[1,0,1]
	v_pk_fma_f32 v[28:29], v[68:69], s[18:19], v[56:57] op_sel_hi:[1,0,1]
	v_pk_fma_f32 v[16:17], v[32:33], s[18:19], v[16:17] op_sel_hi:[1,0,1]
	v_add_u32_e32 v70, s16, v128
	v_ashrrev_i32_e32 v72, 5, v70
	v_add_u32_e32 v71, 0x200, v70
	v_ashrrev_i32_e32 v74, 5, v71
	v_add_u32_e32 v71, 0x400, v70
	v_ashrrev_i32_e32 v76, 5, v71
	v_add_u32_e32 v71, 0x600, v70
	v_ashrrev_i32_e32 v78, 5, v71
	v_ashrrev_i32_e32 v73, 31, v72
	v_lshlrev_b64 v[72:73], 11, v[72:73]
	v_or_b32_e32 v72, v72, v1
	v_lshl_add_u64 v[72:73], s[30:31], 0, v[72:73]
	v_ashrrev_i32_e32 v75, 31, v74
	v_lshlrev_b64 v[74:75], 11, v[74:75]
	v_or_b32_e32 v74, v74, v1
	v_lshl_add_u64 v[74:75], s[30:31], 0, v[74:75]
	v_ashrrev_i32_e32 v77, 31, v76
	v_lshlrev_b64 v[76:77], 11, v[76:77]
	v_or_b32_e32 v76, v76, v1
	v_lshl_add_u64 v[76:77], s[30:31], 0, v[76:77]
	v_ashrrev_i32_e32 v79, 31, v78
	v_lshlrev_b64 v[78:79], 11, v[78:79]
	v_or_b32_e32 v78, v78, v1
	v_lshl_add_u64 v[78:79], s[30:31], 0, v[78:79]
	global_load_dwordx4 v[110:113], v[72:73], off
	global_load_dwordx4 v[114:117], v[74:75], off
	global_load_dwordx4 v[118:121], v[76:77], off
	global_load_dwordx4 v[122:125], v[78:79], off
	global_store_dwordx4 v[34:35], v[2:5], off
	s_nop 1
	v_cvt_pk_bf16_f32 v2, v18, v19
	v_cvt_pk_bf16_f32 v3, v6, v7
	v_cvt_pk_bf16_f32 v4, v20, v21
	v_cvt_pk_bf16_f32 v5, v8, v9
	v_cvt_pk_bf16_f32 v6, v22, v23
	v_cvt_pk_bf16_f32 v7, v10, v11
	v_cvt_pk_bf16_f32 v8, v24, v25
	v_cvt_pk_bf16_f32 v9, v12, v13
	v_cvt_pk_bf16_f32 v10, v26, v27
	v_cvt_pk_bf16_f32 v11, v14, v15
	v_cvt_pk_bf16_f32 v12, v28, v29
	v_cvt_pk_bf16_f32 v13, v16, v17
	global_store_dwordx4 v[36:37], v[2:5], off
	global_store_dwordx4 v[38:39], v[6:9], off
	global_store_dwordx4 v[40:41], v[10:13], off
	v_add_u32_e32 v2, s16, v128
	v_ashrrev_i32_e32 v6, 5, v2
	v_add_u32_e32 v4, 0x200, v2
	v_add_u32_e32 v5, 0x400, v2
	v_add_u32_e32 v8, 0x600, v2
	v_ashrrev_i32_e32 v7, 31, v6
	v_ashrrev_i32_e32 v10, 5, v4
	v_ashrrev_i32_e32 v14, 5, v5
	v_ashrrev_i32_e32 v18, 5, v8
	v_lshlrev_b64 v[20:21], 11, v[6:7]
	v_ashrrev_i32_e32 v11, 31, v10
	v_ashrrev_i32_e32 v15, 31, v14
	v_ashrrev_i32_e32 v19, 31, v18
	v_or_b32_e32 v20, v20, v1
	v_mad_u64_u32 v[16:17], s[22:23], v18, s40, v[0:1]
	v_lshlrev_b64 v[22:23], 11, v[10:11]
	v_lshlrev_b64 v[24:25], 11, v[14:15]
	v_lshlrev_b64 v[26:27], 11, v[18:19]
	v_lshl_add_u64 v[18:19], s[30:31], 0, v[20:21]
	v_lshl_add_u64 v[34:35], s[26:27], 0, v[20:21]
	v_or_b32_e32 v22, v22, v1
	v_or_b32_e32 v24, v24, v1
	v_or_b32_e32 v26, v26, v1
	v_mad_u64_u32 v[2:3], s[22:23], v6, s40, v[0:1]
	v_mad_u64_u32 v[6:7], s[22:23], v10, s40, v[0:1]
	v_mad_u64_u32 v[12:13], s[22:23], v14, s40, v[0:1]
	v_lshl_add_u64 v[28:29], s[30:31], 0, v[22:23]
	v_lshl_add_u64 v[30:31], s[30:31], 0, v[24:25]
	v_lshl_add_u64 v[32:33], s[30:31], 0, v[26:27]
	ds_read_b128 v[2:5], v2
	ds_read_b128 v[6:9], v6
	ds_read_b128 v[10:13], v12
	ds_read_b128 v[14:17], v16
	v_lshl_add_u64 v[36:37], s[26:27], 0, v[22:23]
	v_lshl_add_u64 v[38:39], s[26:27], 0, v[24:25]
	v_lshl_add_u64 v[40:41], s[26:27], 0, v[26:27]
	s_nop 0
	s_nop 0
	s_waitcnt lgkmcnt(3)
	v_lshlrev_b32_e32 v42, 16, v2
	v_and_b32_e32 v43, 0xffff0000, v2
	v_lshlrev_b32_e32 v2, 16, v3
	v_and_b32_e32 v3, 0xffff0000, v3
	v_lshlrev_b32_e32 v44, 16, v4
	v_and_b32_e32 v45, 0xffff0000, v4
	v_lshlrev_b32_e32 v4, 16, v5
	v_and_b32_e32 v5, 0xffff0000, v5
	s_waitcnt lgkmcnt(2)
	v_lshlrev_b32_e32 v46, 16, v6
	v_and_b32_e32 v47, 0xffff0000, v6
	v_lshlrev_b32_e32 v6, 16, v7
	v_and_b32_e32 v7, 0xffff0000, v7
	v_lshlrev_b32_e32 v48, 16, v8
	v_and_b32_e32 v49, 0xffff0000, v8
	v_lshlrev_b32_e32 v8, 16, v9
	v_and_b32_e32 v9, 0xffff0000, v9
	s_addk_i32 s16, 0x800
	s_waitcnt lgkmcnt(1)
	v_lshlrev_b32_e32 v50, 16, v10
	v_and_b32_e32 v51, 0xffff0000, v10
	v_lshlrev_b32_e32 v10, 16, v11
	v_and_b32_e32 v11, 0xffff0000, v11
	v_lshlrev_b32_e32 v52, 16, v12
	v_and_b32_e32 v53, 0xffff0000, v12
	v_lshlrev_b32_e32 v12, 16, v13
	v_and_b32_e32 v13, 0xffff0000, v13
	s_waitcnt lgkmcnt(0)
	v_lshlrev_b32_e32 v54, 16, v14
	v_and_b32_e32 v55, 0xffff0000, v14
	v_lshlrev_b32_e32 v14, 16, v15
	v_and_b32_e32 v15, 0xffff0000, v15
	v_lshlrev_b32_e32 v56, 16, v16
	v_and_b32_e32 v57, 0xffff0000, v16
	v_lshlrev_b32_e32 v16, 16, v17
	v_and_b32_e32 v17, 0xffff0000, v17
	s_waitcnt vmcnt(7)
; DI unsigned pack2(float a, float b) { const f32x2 v = {a, b}; return __builtin_bit_cast(unsigned, __builtin_convertvector(v, bf16v2)); }
; template <int SWAP, int MODE>
; DI void epilogue8(const f32x4 (&acc)[2][2][4][2], char* lds, u16* __restrict__ dst, size_t ld, const u16* __restrict__ Hres) {
;     ...
; #pragma unroll 4
;   for (int i = 0; i < 16; ++i) {
;     const int q = tid + 512 * i, r = q >> 5, c8 = (q & 31) * 8;
;     uint4 v = *(const uint4*)(Ct + r * CT_LD + c8);
;     const size_t o = (size_t)r * ld + c8;
;     if (MODE == 1) {
;       const uint4 hv = *(const uint4*)(Hres + o);
;       float y[8], hx[8]; unpack8(v, y); unpack8(hv, hx);
;       v.x = pack2(ALPHA * hx[0] + y[0], ALPHA * hx[1] + y[1]); v.y = pack2(ALPHA * hx[2] + y[2], ALPHA * hx[3] + y[3]);
;       v.z = pack2(ALPHA * hx[4] + y[4], ALPHA * hx[5] + y[5]); v.w = pack2(ALPHA * hx[6] + y[6], ALPHA * hx[7] + y[7]);
;     }
;     *(uint4*)(dst + o) = v;
	v_mov_b32_e32 v18, v110
	v_mov_b32_e32 v19, v111
	v_mov_b32_e32 v20, v112
	v_mov_b32_e32 v21, v113
	v_lshlrev_b32_e32 v58, 16, v18
	v_and_b32_e32 v59, 0xffff0000, v18
	v_lshlrev_b32_e32 v18, 16, v19
	v_and_b32_e32 v19, 0xffff0000, v19
	v_lshlrev_b32_e32 v60, 16, v20
	v_and_b32_e32 v61, 0xffff0000, v20
	v_lshlrev_b32_e32 v20, 16, v21
	v_and_b32_e32 v21, 0xffff0000, v21
	v_pk_fma_f32 v[42:43], v[58:59], s[18:19], v[42:43] op_sel_hi:[1,0,1]
	v_pk_fma_f32 v[18:19], v[18:19], s[18:19], v[2:3] op_sel_hi:[1,0,1]
	v_pk_fma_f32 v[44:45], v[60:61], s[18:19], v[44:45] op_sel_hi:[1,0,1]
	v_pk_fma_f32 v[20:21], v[20:21], s[18:19], v[4:5] op_sel_hi:[1,0,1]
	v_cvt_pk_bf16_f32 v2, v42, v43
	v_cvt_pk_bf16_f32 v3, v18, v19
	v_cvt_pk_bf16_f32 v4, v44, v45
	s_waitcnt vmcnt(6)
	v_mov_b32_e32 v22, v114
	v_mov_b32_e32 v23, v115
	v_mov_b32_e32 v24, v116
	v_mov_b32_e32 v25, v117
	v_lshlrev_b32_e32 v58, 16, v22
	v_and_b32_e32 v59, 0xffff0000, v22
	v_lshlrev_b32_e32 v22, 16, v23
	v_and_b32_e32 v23, 0xffff0000, v23
	v_lshlrev_b32_e32 v60, 16, v24
	v_and_b32_e32 v61, 0xffff0000, v24
	v_lshlrev_b32_e32 v24, 16, v25
	v_and_b32_e32 v25, 0xffff0000, v25
	s_waitcnt vmcnt(5)
	v_mov_b32_e32 v26, v118
	v_mov_b32_e32 v27, v119
	v_mov_b32_e32 v28, v120
	v_mov_b32_e32 v29, v121
	v_lshlrev_b32_e32 v62, 16, v26
	v_and_b32_e32 v63, 0xffff0000, v26
	v_lshlrev_b32_e32 v26, 16, v27
	v_and_b32_e32 v27, 0xffff0000, v27
	v_lshlrev_b32_e32 v64, 16, v28
	v_and_b32_e32 v65, 0xffff0000, v28
	v_lshlrev_b32_e32 v28, 16, v29
	v_and_b32_e32 v29, 0xffff0000, v29
	s_waitcnt vmcnt(4)
	v_mov_b32_e32 v30, v122
	v_mov_b32_e32 v31, v123
	v_mov_b32_e32 v32, v124
	v_mov_b32_e32 v33, v125
	v_lshlrev_b32_e32 v66, 16, v30
	v_and_b32_e32 v67, 0xffff0000, v30
	v_lshlrev_b32_e32 v30, 16, v31
	v_and_b32_e32 v31, 0xffff0000, v31
	v_lshlrev_b32_e32 v68, 16, v32
	v_and_b32_e32 v69, 0xffff0000, v32
	v_lshlrev_b32_e32 v32, 16, v33
	v_and_b32_e32 v33, 0xffff0000, v33
	v_cvt_pk_bf16_f32 v5, v20, v21
	v_pk_fma_f32 v[18:19], v[58:59], s[18:19], v[46:47] op_sel_hi:[1,0,1]
	v_pk_fma_f32 v[6:7], v[22:23], s[18:19], v[6:7] op_sel_hi:[1,0,1]
	v_pk_fma_f32 v[20:21], v[60:61], s[18:19], v[48:49] op_sel_hi:[1,0,1]
	v_pk_fma_f32 v[8:9], v[24:25], s[18:19], v[8:9] op_sel_hi:[1,0,1]
	v_pk_fma_f32 v[22:23], v[62:63], s[18:19], v[50:51] op_sel_hi:[1,0,1]
	v_pk_fma_f32 v[10:11], v[26:27], s[18:19], v[10:11] op_sel_hi:[1,0,1]
	v_pk_fma_f32 v[24:25], v[64:65], s[18:19], v[52:53] op_sel_hi:[1,0,1]
	v_pk_fma_f32 v[12:13], v[28:29], s[18:19], v[12:13] op_sel_hi:[1,0,1]
	v_pk_fma_f32 v[26:27], v[66:67], s[18:19], v[54:55] op_sel_hi:[1,0,1]
	v_pk_fma_f32 v[14:15], v[30:31], s[18:19], v[14:15] op_sel_hi:[1,0,1]
	v_pk_fma_f32 v[28:29], v[68:69], s[18:19], v[56:57] op_sel_hi:[1,0,1]
	v_pk_fma_f32 v[16:17], v[32:33], s[18:19], v[16:17] op_sel_hi:[1,0,1]
	v_add_u32_e32 v70, s16, v128
	v_ashrrev_i32_e32 v72, 5, v70
	v_add_u32_e32 v71, 0x200, v70
	v_ashrrev_i32_e32 v74, 5, v71
	v_add_u32_e32 v71, 0x400, v70
	v_ashrrev_i32_e32 v76, 5, v71
	v_add_u32_e32 v71, 0x600, v70
	v_ashrrev_i32_e32 v78, 5, v71
	v_ashrrev_i32_e32 v73, 31, v72
	v_lshlrev_b64 v[72:73], 11, v[72:73]
	v_or_b32_e32 v72, v72, v1
	v_lshl_add_u64 v[72:73], s[30:31], 0, v[72:73]
	v_ashrrev_i32_e32 v75, 31, v74
	v_lshlrev_b64 v[74:75], 11, v[74:75]
	v_or_b32_e32 v74, v74, v1
	v_lshl_add_u64 v[74:75], s[30:31], 0, v[74:75]
	v_ashrrev_i32_e32 v77, 31, v76
	v_lshlrev_b64 v[76:77], 11, v[76:77]
	v_or_b32_e32 v76, v76, v1
	v_lshl_add_u64 v[76:77], s[30:31], 0, v[76:77]
	v_ashrrev_i32_e32 v79, 31, v78
	v_lshlrev_b64 v[78:79], 11, v[78:79]
	v_or_b32_e32 v78, v78, v1
	v_lshl_add_u64 v[78:79], s[30:31], 0, v[78:79]
	global_load_dwordx4 v[94:97], v[72:73], off
	global_load_dwordx4 v[98:101], v[74:75], off
	global_load_dwordx4 v[102:105], v[76:77], off
	global_load_dwordx4 v[106:109], v[78:79], off
	global_store_dwordx4 v[34:35], v[2:5], off
	s_nop 1
	v_cvt_pk_bf16_f32 v2, v18, v19
	v_cvt_pk_bf16_f32 v3, v6, v7
	v_cvt_pk_bf16_f32 v4, v20, v21
	v_cvt_pk_bf16_f32 v5, v8, v9
	v_cvt_pk_bf16_f32 v6, v22, v23
	v_cvt_pk_bf16_f32 v7, v10, v11
	v_cvt_pk_bf16_f32 v8, v24, v25
	v_cvt_pk_bf16_f32 v9, v12, v13
	v_cvt_pk_bf16_f32 v10, v26, v27
	v_cvt_pk_bf16_f32 v11, v14, v15
	v_cvt_pk_bf16_f32 v12, v28, v29
	v_cvt_pk_bf16_f32 v13, v16, v17
	global_store_dwordx4 v[36:37], v[2:5], off
	global_store_dwordx4 v[38:39], v[6:9], off
	global_store_dwordx4 v[40:41], v[10:13], off
	v_add_u32_e32 v2, s16, v128
	v_ashrrev_i32_e32 v6, 5, v2
	v_add_u32_e32 v4, 0x200, v2
	v_add_u32_e32 v5, 0x400, v2
	v_add_u32_e32 v8, 0x600, v2
	v_ashrrev_i32_e32 v7, 31, v6
	v_ashrrev_i32_e32 v10, 5, v4
	v_ashrrev_i32_e32 v14, 5, v5
	v_ashrrev_i32_e32 v18, 5, v8
	v_lshlrev_b64 v[20:21], 11, v[6:7]
	v_ashrrev_i32_e32 v11, 31, v10
	v_ashrrev_i32_e32 v15, 31, v14
	v_ashrrev_i32_e32 v19, 31, v18
	v_or_b32_e32 v20, v20, v1
	v_mad_u64_u32 v[16:17], s[22:23], v18, s40, v[0:1]
	v_lshlrev_b64 v[22:23], 11, v[10:11]
	v_lshlrev_b64 v[24:25], 11, v[14:15]
	v_lshlrev_b64 v[26:27], 11, v[18:19]
	v_lshl_add_u64 v[18:19], s[30:31], 0, v[20:21]
	v_lshl_add_u64 v[34:35], s[26:27], 0, v[20:21]
	v_or_b32_e32 v22, v22, v1
	v_or_b32_e32 v24, v24, v1
	v_or_b32_e32 v26, v26, v1
	v_mad_u64_u32 v[2:3], s[22:23], v6, s40, v[0:1]
	v_mad_u64_u32 v[6:7], s[22:23], v10, s40, v[0:1]
	v_mad_u64_u32 v[12:13], s[22:23], v14, s40, v[0:1]
	v_lshl_add_u64 v[28:29], s[30:31], 0, v[22:23]
	v_lshl_add_u64 v[30:31], s[30:31], 0, v[24:25]
	v_lshl_add_u64 v[32:33], s[30:31], 0, v[26:27]
	ds_read_b128 v[2:5], v2
	ds_read_b128 v[6:9], v6
	ds_read_b128 v[10:13], v12
	ds_read_b128 v[14:17], v16
	v_lshl_add_u64 v[36:37], s[26:27], 0, v[22:23]
	v_lshl_add_u64 v[38:39], s[26:27], 0, v[24:25]
	v_lshl_add_u64 v[40:41], s[26:27], 0, v[26:27]
	s_nop 0
	s_nop 0
	s_waitcnt lgkmcnt(3)
; DI unsigned pack2(float a, float b) { const f32x2 v = {a, b}; return __builtin_bit_cast(unsigned, __builtin_convertvector(v, bf16v2)); }
; template <int SWAP, int MODE>
; DI void epilogue8(const f32x4 (&acc)[2][2][4][2], char* lds, u16* __restrict__ dst, size_t ld, const u16* __restrict__ Hres) {
;     ...
; #pragma unroll 4
;   for (int i = 0; i < 16; ++i) {
;     const int q = tid + 512 * i, r = q >> 5, c8 = (q & 31) * 8;
;     uint4 v = *(const uint4*)(Ct + r * CT_LD + c8);
;     const size_t o = (size_t)r * ld + c8;
;     if (MODE == 1) {
;       const uint4 hv = *(const uint4*)(Hres + o);
;       float y[8], hx[8]; unpack8(v, y); unpack8(hv, hx);
;       v.x = pack2(ALPHA * hx[0] + y[0], ALPHA * hx[1] + y[1]); v.y = pack2(ALPHA * hx[2] + y[2], ALPHA * hx[3] + y[3]);
;       v.z = pack2(ALPHA * hx[4] + y[4], ALPHA * hx[5] + y[5]); v.w = pack2(ALPHA * hx[6] + y[6], ALPHA * hx[7] + y[7]);
;     }
;     *(uint4*)(dst + o) = v;
	v_lshlrev_b32_e32 v42, 16, v2
	v_and_b32_e32 v43, 0xffff0000, v2
	v_lshlrev_b32_e32 v2, 16, v3
	v_and_b32_e32 v3, 0xffff0000, v3
	v_lshlrev_b32_e32 v44, 16, v4
	v_and_b32_e32 v45, 0xffff0000, v4
	v_lshlrev_b32_e32 v4, 16, v5
	v_and_b32_e32 v5, 0xffff0000, v5
	s_waitcnt lgkmcnt(2)
	v_lshlrev_b32_e32 v46, 16, v6
	v_and_b32_e32 v47, 0xffff0000, v6
	v_lshlrev_b32_e32 v6, 16, v7
	v_and_b32_e32 v7, 0xffff0000, v7
	v_lshlrev_b32_e32 v48, 16, v8
	v_and_b32_e32 v49, 0xffff0000, v8
	v_lshlrev_b32_e32 v8, 16, v9
	v_and_b32_e32 v9, 0xffff0000, v9
	s_addk_i32 s16, 0x800
	s_waitcnt lgkmcnt(1)
	v_lshlrev_b32_e32 v50, 16, v10
	v_and_b32_e32 v51, 0xffff0000, v10
	v_lshlrev_b32_e32 v10, 16, v11
	v_and_b32_e32 v11, 0xffff0000, v11
	v_lshlrev_b32_e32 v52, 16, v12
	v_and_b32_e32 v53, 0xffff0000, v12
	v_lshlrev_b32_e32 v12, 16, v13
	v_and_b32_e32 v13, 0xffff0000, v13
	s_waitcnt lgkmcnt(0)
	v_lshlrev_b32_e32 v54, 16, v14
	v_and_b32_e32 v55, 0xffff0000, v14
	v_lshlrev_b32_e32 v14, 16, v15
	v_and_b32_e32 v15, 0xffff0000, v15
	v_lshlrev_b32_e32 v56, 16, v16
	v_and_b32_e32 v57, 0xffff0000, v16
	v_lshlrev_b32_e32 v16, 16, v17
	v_and_b32_e32 v17, 0xffff0000, v17
	s_waitcnt vmcnt(7)
	v_mov_b32_e32 v18, v94
	v_mov_b32_e32 v19, v95
	v_mov_b32_e32 v20, v96
	v_mov_b32_e32 v21, v97
	v_lshlrev_b32_e32 v58, 16, v18
	v_and_b32_e32 v59, 0xffff0000, v18
	v_lshlrev_b32_e32 v18, 16, v19
	v_and_b32_e32 v19, 0xffff0000, v19
	v_lshlrev_b32_e32 v60, 16, v20
	v_and_b32_e32 v61, 0xffff0000, v20
	v_lshlrev_b32_e32 v20, 16, v21
	v_and_b32_e32 v21, 0xffff0000, v21
	v_pk_fma_f32 v[42:43], v[58:59], s[18:19], v[42:43] op_sel_hi:[1,0,1]
	v_pk_fma_f32 v[18:19], v[18:19], s[18:19], v[2:3] op_sel_hi:[1,0,1]
	v_pk_fma_f32 v[44:45], v[60:61], s[18:19], v[44:45] op_sel_hi:[1,0,1]
	v_pk_fma_f32 v[20:21], v[20:21], s[18:19], v[4:5] op_sel_hi:[1,0,1]
	v_cvt_pk_bf16_f32 v2, v42, v43
	v_cvt_pk_bf16_f32 v3, v18, v19
	v_cvt_pk_bf16_f32 v4, v44, v45
	s_waitcnt vmcnt(6)
	v_mov_b32_e32 v22, v98
	v_mov_b32_e32 v23, v99
	v_mov_b32_e32 v24, v100
	v_mov_b32_e32 v25, v101
	v_lshlrev_b32_e32 v58, 16, v22
	v_and_b32_e32 v59, 0xffff0000, v22
	v_lshlrev_b32_e32 v22, 16, v23
	v_and_b32_e32 v23, 0xffff0000, v23
	v_lshlrev_b32_e32 v60, 16, v24
	v_and_b32_e32 v61, 0xffff0000, v24
	v_lshlrev_b32_e32 v24, 16, v25
	v_and_b32_e32 v25, 0xffff0000, v25
	s_waitcnt vmcnt(5)
	v_mov_b32_e32 v26, v102
	v_mov_b32_e32 v27, v103
	v_mov_b32_e32 v28, v104
	v_mov_b32_e32 v29, v105
	v_lshlrev_b32_e32 v62, 16, v26
	v_and_b32_e32 v63, 0xffff0000, v26
	v_lshlrev_b32_e32 v26, 16, v27
	v_and_b32_e32 v27, 0xffff0000, v27
	v_lshlrev_b32_e32 v64, 16, v28
	v_and_b32_e32 v65, 0xffff0000, v28
	v_lshlrev_b32_e32 v28, 16, v29
	v_and_b32_e32 v29, 0xffff0000, v29
	s_waitcnt vmcnt(4)
	v_mov_b32_e32 v30, v106
	v_mov_b32_e32 v31, v107
	v_mov_b32_e32 v32, v108
	v_mov_b32_e32 v33, v109
	v_lshlrev_b32_e32 v66, 16, v30
	v_and_b32_e32 v67, 0xffff0000, v30
	v_lshlrev_b32_e32 v30, 16, v31
	v_and_b32_e32 v31, 0xffff0000, v31
	v_lshlrev_b32_e32 v68, 16, v32
	v_and_b32_e32 v69, 0xffff0000, v32
	v_lshlrev_b32_e32 v32, 16, v33
	v_and_b32_e32 v33, 0xffff0000, v33
	v_cvt_pk_bf16_f32 v5, v20, v21
	v_pk_fma_f32 v[18:19], v[58:59], s[18:19], v[46:47] op_sel_hi:[1,0,1]
	v_pk_fma_f32 v[6:7], v[22:23], s[18:19], v[6:7] op_sel_hi:[1,0,1]
	v_pk_fma_f32 v[20:21], v[60:61], s[18:19], v[48:49] op_sel_hi:[1,0,1]
	v_pk_fma_f32 v[8:9], v[24:25], s[18:19], v[8:9] op_sel_hi:[1,0,1]
	v_pk_fma_f32 v[22:23], v[62:63], s[18:19], v[50:51] op_sel_hi:[1,0,1]
	v_pk_fma_f32 v[10:11], v[26:27], s[18:19], v[10:11] op_sel_hi:[1,0,1]
	v_pk_fma_f32 v[24:25], v[64:65], s[18:19], v[52:53] op_sel_hi:[1,0,1]
	v_pk_fma_f32 v[12:13], v[28:29], s[18:19], v[12:13] op_sel_hi:[1,0,1]
	v_pk_fma_f32 v[26:27], v[66:67], s[18:19], v[54:55] op_sel_hi:[1,0,1]
	v_pk_fma_f32 v[14:15], v[30:31], s[18:19], v[14:15] op_sel_hi:[1,0,1]
	v_pk_fma_f32 v[28:29], v[68:69], s[18:19], v[56:57] op_sel_hi:[1,0,1]
	v_pk_fma_f32 v[16:17], v[32:33], s[18:19], v[16:17] op_sel_hi:[1,0,1]
	v_add_u32_e32 v70, s16, v128
	v_ashrrev_i32_e32 v72, 5, v70
	v_add_u32_e32 v71, 0x200, v70
	v_ashrrev_i32_e32 v74, 5, v71
	v_add_u32_e32 v71, 0x400, v70
	v_ashrrev_i32_e32 v76, 5, v71
	v_add_u32_e32 v71, 0x600, v70
	v_ashrrev_i32_e32 v78, 5, v71
	v_ashrrev_i32_e32 v73, 31, v72
	v_lshlrev_b64 v[72:73], 11, v[72:73]
	v_or_b32_e32 v72, v72, v1
	v_lshl_add_u64 v[72:73], s[30:31], 0, v[72:73]
	v_ashrrev_i32_e32 v75, 31, v74
	v_lshlrev_b64 v[74:75], 11, v[74:75]
	v_or_b32_e32 v74, v74, v1
	v_lshl_add_u64 v[74:75], s[30:31], 0, v[74:75]
	v_ashrrev_i32_e32 v77, 31, v76
	v_lshlrev_b64 v[76:77], 11, v[76:77]
	v_or_b32_e32 v76, v76, v1
	v_lshl_add_u64 v[76:77], s[30:31], 0, v[76:77]
	v_ashrrev_i32_e32 v79, 31, v78
	v_lshlrev_b64 v[78:79], 11, v[78:79]
	v_or_b32_e32 v78, v78, v1
	v_lshl_add_u64 v[78:79], s[30:31], 0, v[78:79]
	global_load_dwordx4 v[110:113], v[72:73], off
	global_load_dwordx4 v[114:117], v[74:75], off
	global_load_dwordx4 v[118:121], v[76:77], off
	global_load_dwordx4 v[122:125], v[78:79], off
	global_store_dwordx4 v[34:35], v[2:5], off
	s_nop 1
	v_cvt_pk_bf16_f32 v2, v18, v19
	v_cvt_pk_bf16_f32 v3, v6, v7
	v_cvt_pk_bf16_f32 v4, v20, v21
	v_cvt_pk_bf16_f32 v5, v8, v9
	v_cvt_pk_bf16_f32 v6, v22, v23
	v_cvt_pk_bf16_f32 v7, v10, v11
	v_cvt_pk_bf16_f32 v8, v24, v25
	v_cvt_pk_bf16_f32 v9, v12, v13
	v_cvt_pk_bf16_f32 v10, v26, v27
	v_cvt_pk_bf16_f32 v11, v14, v15
	v_cvt_pk_bf16_f32 v12, v28, v29
	v_cvt_pk_bf16_f32 v13, v16, v17
	global_store_dwordx4 v[36:37], v[2:5], off
	global_store_dwordx4 v[38:39], v[6:9], off
	global_store_dwordx4 v[40:41], v[10:13], off
	v_add_u32_e32 v2, s16, v128
	v_ashrrev_i32_e32 v6, 5, v2
	v_add_u32_e32 v4, 0x200, v2
	v_add_u32_e32 v5, 0x400, v2
	v_add_u32_e32 v8, 0x600, v2
	v_ashrrev_i32_e32 v7, 31, v6
	v_ashrrev_i32_e32 v10, 5, v4
	v_ashrrev_i32_e32 v14, 5, v5
	v_ashrrev_i32_e32 v18, 5, v8
	v_lshlrev_b64 v[20:21], 11, v[6:7]
	v_ashrrev_i32_e32 v11, 31, v10
	v_ashrrev_i32_e32 v15, 31, v14
	v_ashrrev_i32_e32 v19, 31, v18
	v_or_b32_e32 v20, v20, v1
	v_mad_u64_u32 v[16:17], s[22:23], v18, s40, v[0:1]
	v_lshlrev_b64 v[22:23], 11, v[10:11]
	v_lshlrev_b64 v[24:25], 11, v[14:15]
	v_lshlrev_b64 v[26:27], 11, v[18:19]
	v_lshl_add_u64 v[18:19], s[30:31], 0, v[20:21]
	v_lshl_add_u64 v[34:35], s[26:27], 0, v[20:21]
	v_or_b32_e32 v22, v22, v1
	v_or_b32_e32 v24, v24, v1
	v_or_b32_e32 v26, v26, v1
	v_mad_u64_u32 v[2:3], s[22:23], v6, s40, v[0:1]
	v_mad_u64_u32 v[6:7], s[22:23], v10, s40, v[0:1]
	v_mad_u64_u32 v[12:13], s[22:23], v14, s40, v[0:1]
	v_lshl_add_u64 v[28:29], s[30:31], 0, v[22:23]
	v_lshl_add_u64 v[30:31], s[30:31], 0, v[24:25]
	v_lshl_add_u64 v[32:33], s[30:31], 0, v[26:27]
	ds_read_b128 v[2:5], v2
	ds_read_b128 v[6:9], v6
	ds_read_b128 v[10:13], v12
	ds_read_b128 v[14:17], v16
	v_lshl_add_u64 v[36:37], s[26:27], 0, v[22:23]
	v_lshl_add_u64 v[38:39], s[26:27], 0, v[24:25]
	v_lshl_add_u64 v[40:41], s[26:27], 0, v[26:27]
	s_nop 0
	s_nop 0
	s_waitcnt lgkmcnt(3)
; DI unsigned pack2(float a, float b) { const f32x2 v = {a, b}; return __builtin_bit_cast(unsigned, __builtin_convertvector(v, bf16v2)); }
; template <int SWAP, int MODE>
; DI void epilogue8(const f32x4 (&acc)[2][2][4][2], char* lds, u16* __restrict__ dst, size_t ld, const u16* __restrict__ Hres) {
;     ...
; #pragma unroll 4
;   for (int i = 0; i < 16; ++i) {
;     const int q = tid + 512 * i, r = q >> 5, c8 = (q & 31) * 8;
;     uint4 v = *(const uint4*)(Ct + r * CT_LD + c8);
;     const size_t o = (size_t)r * ld + c8;
;     if (MODE == 1) {
;       const uint4 hv = *(const uint4*)(Hres + o);
;       float y[8], hx[8]; unpack8(v, y); unpack8(hv, hx);
;       v.x = pack2(ALPHA * hx[0] + y[0], ALPHA * hx[1] + y[1]); v.y = pack2(ALPHA * hx[2] + y[2], ALPHA * hx[3] + y[3]);
;       v.z = pack2(ALPHA * hx[4] + y[4], ALPHA * hx[5] + y[5]); v.w = pack2(ALPHA * hx[6] + y[6], ALPHA * hx[7] + y[7]);
;     }
;     *(uint4*)(dst + o) = v;
;   }
;   __syncthreads();
	v_lshlrev_b32_e32 v42, 16, v2
	v_and_b32_e32 v43, 0xffff0000, v2
	v_lshlrev_b32_e32 v2, 16, v3
	v_and_b32_e32 v3, 0xffff0000, v3
	v_lshlrev_b32_e32 v44, 16, v4
	v_and_b32_e32 v45, 0xffff0000, v4
	v_lshlrev_b32_e32 v4, 16, v5
	v_and_b32_e32 v5, 0xffff0000, v5
	s_waitcnt lgkmcnt(2)
	v_lshlrev_b32_e32 v46, 16, v6
	v_and_b32_e32 v47, 0xffff0000, v6
	v_lshlrev_b32_e32 v6, 16, v7
	v_and_b32_e32 v7, 0xffff0000, v7
	v_lshlrev_b32_e32 v48, 16, v8
	v_and_b32_e32 v49, 0xffff0000, v8
	v_lshlrev_b32_e32 v8, 16, v9
	v_and_b32_e32 v9, 0xffff0000, v9
	s_addk_i32 s16, 0x800
	s_waitcnt lgkmcnt(1)
	v_lshlrev_b32_e32 v50, 16, v10
	v_and_b32_e32 v51, 0xffff0000, v10
	v_lshlrev_b32_e32 v10, 16, v11
	v_and_b32_e32 v11, 0xffff0000, v11
	v_lshlrev_b32_e32 v52, 16, v12
	v_and_b32_e32 v53, 0xffff0000, v12
	v_lshlrev_b32_e32 v12, 16, v13
	v_and_b32_e32 v13, 0xffff0000, v13
	s_waitcnt lgkmcnt(0)
	v_lshlrev_b32_e32 v54, 16, v14
	v_and_b32_e32 v55, 0xffff0000, v14
	v_lshlrev_b32_e32 v14, 16, v15
	v_and_b32_e32 v15, 0xffff0000, v15
	v_lshlrev_b32_e32 v56, 16, v16
	v_and_b32_e32 v57, 0xffff0000, v16
	v_lshlrev_b32_e32 v16, 16, v17
	v_and_b32_e32 v17, 0xffff0000, v17
	s_waitcnt vmcnt(7)
	v_mov_b32_e32 v18, v110
	v_mov_b32_e32 v19, v111
	v_mov_b32_e32 v20, v112
	v_mov_b32_e32 v21, v113
	v_lshlrev_b32_e32 v58, 16, v18
	v_and_b32_e32 v59, 0xffff0000, v18
	v_lshlrev_b32_e32 v18, 16, v19
	v_and_b32_e32 v19, 0xffff0000, v19
	v_lshlrev_b32_e32 v60, 16, v20
	v_and_b32_e32 v61, 0xffff0000, v20
	v_lshlrev_b32_e32 v20, 16, v21
	v_and_b32_e32 v21, 0xffff0000, v21
	v_pk_fma_f32 v[42:43], v[58:59], s[18:19], v[42:43] op_sel_hi:[1,0,1]
	v_pk_fma_f32 v[18:19], v[18:19], s[18:19], v[2:3] op_sel_hi:[1,0,1]
	v_pk_fma_f32 v[44:45], v[60:61], s[18:19], v[44:45] op_sel_hi:[1,0,1]
	v_pk_fma_f32 v[20:21], v[20:21], s[18:19], v[4:5] op_sel_hi:[1,0,1]
	v_cvt_pk_bf16_f32 v2, v42, v43
	v_cvt_pk_bf16_f32 v3, v18, v19
	v_cvt_pk_bf16_f32 v4, v44, v45
	s_waitcnt vmcnt(6)
	v_mov_b32_e32 v22, v114
	v_mov_b32_e32 v23, v115
	v_mov_b32_e32 v24, v116
	v_mov_b32_e32 v25, v117
	v_lshlrev_b32_e32 v58, 16, v22
	v_and_b32_e32 v59, 0xffff0000, v22
	v_lshlrev_b32_e32 v22, 16, v23
	v_and_b32_e32 v23, 0xffff0000, v23
	v_lshlrev_b32_e32 v60, 16, v24
	v_and_b32_e32 v61, 0xffff0000, v24
	v_lshlrev_b32_e32 v24, 16, v25
	v_and_b32_e32 v25, 0xffff0000, v25
	s_waitcnt vmcnt(5)
	v_mov_b32_e32 v26, v118
	v_mov_b32_e32 v27, v119
	v_mov_b32_e32 v28, v120
	v_mov_b32_e32 v29, v121
	v_lshlrev_b32_e32 v62, 16, v26
	v_and_b32_e32 v63, 0xffff0000, v26
	v_lshlrev_b32_e32 v26, 16, v27
	v_and_b32_e32 v27, 0xffff0000, v27
	v_lshlrev_b32_e32 v64, 16, v28
	v_and_b32_e32 v65, 0xffff0000, v28
	v_lshlrev_b32_e32 v28, 16, v29
	v_and_b32_e32 v29, 0xffff0000, v29
	s_waitcnt vmcnt(4)
	v_mov_b32_e32 v30, v122
	v_mov_b32_e32 v31, v123
	v_mov_b32_e32 v32, v124
	v_mov_b32_e32 v33, v125
	v_lshlrev_b32_e32 v66, 16, v30
	v_and_b32_e32 v67, 0xffff0000, v30
	v_lshlrev_b32_e32 v30, 16, v31
	v_and_b32_e32 v31, 0xffff0000, v31
	v_lshlrev_b32_e32 v68, 16, v32
	v_and_b32_e32 v69, 0xffff0000, v32
	v_lshlrev_b32_e32 v32, 16, v33
	v_and_b32_e32 v33, 0xffff0000, v33
	v_cvt_pk_bf16_f32 v5, v20, v21
	v_pk_fma_f32 v[18:19], v[58:59], s[18:19], v[46:47] op_sel_hi:[1,0,1]
	v_pk_fma_f32 v[6:7], v[22:23], s[18:19], v[6:7] op_sel_hi:[1,0,1]
	v_pk_fma_f32 v[20:21], v[60:61], s[18:19], v[48:49] op_sel_hi:[1,0,1]
	v_pk_fma_f32 v[8:9], v[24:25], s[18:19], v[8:9] op_sel_hi:[1,0,1]
	v_pk_fma_f32 v[22:23], v[62:63], s[18:19], v[50:51] op_sel_hi:[1,0,1]
	v_pk_fma_f32 v[10:11], v[26:27], s[18:19], v[10:11] op_sel_hi:[1,0,1]
	v_pk_fma_f32 v[24:25], v[64:65], s[18:19], v[52:53] op_sel_hi:[1,0,1]
	v_pk_fma_f32 v[12:13], v[28:29], s[18:19], v[12:13] op_sel_hi:[1,0,1]
	v_pk_fma_f32 v[26:27], v[66:67], s[18:19], v[54:55] op_sel_hi:[1,0,1]
	v_pk_fma_f32 v[14:15], v[30:31], s[18:19], v[14:15] op_sel_hi:[1,0,1]
	v_pk_fma_f32 v[28:29], v[68:69], s[18:19], v[56:57] op_sel_hi:[1,0,1]
	v_pk_fma_f32 v[16:17], v[32:33], s[18:19], v[16:17] op_sel_hi:[1,0,1]
	global_store_dwordx4 v[34:35], v[2:5], off
	s_nop 1
	v_cvt_pk_bf16_f32 v2, v18, v19
	v_cvt_pk_bf16_f32 v3, v6, v7
	v_cvt_pk_bf16_f32 v4, v20, v21
	v_cvt_pk_bf16_f32 v5, v8, v9
	v_cvt_pk_bf16_f32 v6, v22, v23
	v_cvt_pk_bf16_f32 v7, v10, v11
	v_cvt_pk_bf16_f32 v8, v24, v25
	v_cvt_pk_bf16_f32 v9, v12, v13
	v_cvt_pk_bf16_f32 v10, v26, v27
	v_cvt_pk_bf16_f32 v11, v14, v15
	v_cvt_pk_bf16_f32 v12, v28, v29
	v_cvt_pk_bf16_f32 v13, v16, v17
	global_store_dwordx4 v[36:37], v[2:5], off
	global_store_dwordx4 v[38:39], v[6:9], off
	global_store_dwordx4 v[40:41], v[10:13], off
	s_andn2_b64 vcc, exec, s[20:21]
	s_mov_b32 s26, s42
	s_mov_b32 s27, s41
	s_mov_b32 s22, s42
	s_mov_b32 s23, s41
	s_barrier
	s_cbranch_vccnz .LBB0_688

; DI unsigned pack2(float a, float b) { const f32x2 v = {a, b}; return __builtin_bit_cast(unsigned, __builtin_convertvector(v, bf16v2)); }
; template <int SWAP, int MODE>
; DI void epilogue8(const f32x4 (&acc)[2][2][4][2], char* lds, u16* __restrict__ dst, size_t ld, const u16* __restrict__ Hres) {
;     ...
; #pragma unroll 4
;   for (int i = 0; i < 16; ++i) {
;     const int q = tid + 512 * i, r = q >> 5, c8 = (q & 31) * 8;
;     uint4 v = *(const uint4*)(Ct + r * CT_LD + c8);
;     const size_t o = (size_t)r * ld + c8;
;     if (MODE == 1) {
;       const uint4 hv = *(const uint4*)(Hres + o);
;       float y[8], hx[8]; unpack8(v, y); unpack8(hv, hx);
;       v.x = pack2(ALPHA * hx[0] + y[0], ALPHA * hx[1] + y[1]); v.y = pack2(ALPHA * hx[2] + y[2], ALPHA * hx[3] + y[3]);
;       v.z = pack2(ALPHA * hx[4] + y[4], ALPHA * hx[5] + y[5]); v.w = pack2(ALPHA * hx[6] + y[6], ALPHA * hx[7] + y[7]);
;     }
;     *(uint4*)(dst + o) = v;
.LBB0_986:
	v_add_u32_e32 v70, s16, v128
	v_ashrrev_i32_e32 v72, 5, v70
	v_add_u32_e32 v71, 0x200, v70
	v_ashrrev_i32_e32 v74, 5, v71
	v_add_u32_e32 v71, 0x400, v70
	v_ashrrev_i32_e32 v76, 5, v71
	v_add_u32_e32 v71, 0x600, v70
	v_ashrrev_i32_e32 v78, 5, v71
	v_ashrrev_i32_e32 v73, 31, v72
	v_lshlrev_b64 v[72:73], 11, v[72:73]
	v_or_b32_e32 v72, v72, v1
	v_lshl_add_u64 v[72:73], s[44:45], 0, v[72:73]
	v_ashrrev_i32_e32 v75, 31, v74
	v_lshlrev_b64 v[74:75], 11, v[74:75]
	v_or_b32_e32 v74, v74, v1
	v_lshl_add_u64 v[74:75], s[44:45], 0, v[74:75]
	v_ashrrev_i32_e32 v77, 31, v76
	v_lshlrev_b64 v[76:77], 11, v[76:77]
	v_or_b32_e32 v76, v76, v1
	v_lshl_add_u64 v[76:77], s[44:45], 0, v[76:77]
	v_ashrrev_i32_e32 v79, 31, v78
	v_lshlrev_b64 v[78:79], 11, v[78:79]
	v_or_b32_e32 v78, v78, v1
	v_lshl_add_u64 v[78:79], s[44:45], 0, v[78:79]
	global_load_dwordx4 v[94:97], v[72:73], off
	global_load_dwordx4 v[98:101], v[74:75], off
	global_load_dwordx4 v[102:105], v[76:77], off
	global_load_dwordx4 v[106:109], v[78:79], off
	v_add_u32_e32 v2, s16, v128
	v_ashrrev_i32_e32 v6, 5, v2
	v_add_u32_e32 v4, 0x200, v2
	v_add_u32_e32 v5, 0x400, v2
	v_add_u32_e32 v8, 0x600, v2
	v_ashrrev_i32_e32 v7, 31, v6
	v_ashrrev_i32_e32 v10, 5, v4
	v_ashrrev_i32_e32 v14, 5, v5
	v_ashrrev_i32_e32 v18, 5, v8
	v_lshlrev_b64 v[20:21], 11, v[6:7]
	v_ashrrev_i32_e32 v11, 31, v10
	v_ashrrev_i32_e32 v15, 31, v14
	v_ashrrev_i32_e32 v19, 31, v18
	v_or_b32_e32 v20, v20, v1
	v_mad_u64_u32 v[16:17], s[22:23], v18, s50, v[0:1]
	v_lshlrev_b64 v[22:23], 11, v[10:11]
	v_lshlrev_b64 v[24:25], 11, v[14:15]
	v_lshlrev_b64 v[26:27], 11, v[18:19]
	v_lshl_add_u64 v[18:19], s[44:45], 0, v[20:21]
	v_lshl_add_u64 v[34:35], s[42:43], 0, v[20:21]
	v_or_b32_e32 v22, v22, v1
	v_or_b32_e32 v24, v24, v1
	v_or_b32_e32 v26, v26, v1
	v_mad_u64_u32 v[2:3], s[22:23], v6, s50, v[0:1]
	v_mad_u64_u32 v[6:7], s[22:23], v10, s50, v[0:1]
	v_mad_u64_u32 v[12:13], s[22:23], v14, s50, v[0:1]
	v_lshl_add_u64 v[28:29], s[44:45], 0, v[22:23]
	v_lshl_add_u64 v[30:31], s[44:45], 0, v[24:25]
	v_lshl_add_u64 v[32:33], s[44:45], 0, v[26:27]
	ds_read_b128 v[2:5], v2
	ds_read_b128 v[6:9], v6
	ds_read_b128 v[10:13], v12
	ds_read_b128 v[14:17], v16
	v_lshl_add_u64 v[36:37], s[42:43], 0, v[22:23]
	v_lshl_add_u64 v[38:39], s[42:43], 0, v[24:25]
	v_lshl_add_u64 v[40:41], s[42:43], 0, v[26:27]
	s_nop 0
	s_nop 0
	s_waitcnt lgkmcnt(3)
	v_lshlrev_b32_e32 v42, 16, v2
	v_and_b32_e32 v43, 0xffff0000, v2
	v_lshlrev_b32_e32 v2, 16, v3
	v_and_b32_e32 v3, 0xffff0000, v3
	v_lshlrev_b32_e32 v44, 16, v4
	v_and_b32_e32 v45, 0xffff0000, v4
	v_lshlrev_b32_e32 v4, 16, v5
	v_and_b32_e32 v5, 0xffff0000, v5
	s_waitcnt lgkmcnt(2)
	v_lshlrev_b32_e32 v46, 16, v6
	v_and_b32_e32 v47, 0xffff0000, v6
	v_lshlrev_b32_e32 v6, 16, v7
	v_and_b32_e32 v7, 0xffff0000, v7
	v_lshlrev_b32_e32 v48, 16, v8
	v_and_b32_e32 v49, 0xffff0000, v8
	v_lshlrev_b32_e32 v8, 16, v9
	v_and_b32_e32 v9, 0xffff0000, v9
	s_addk_i32 s16, 0x800
	s_waitcnt lgkmcnt(1)
	v_lshlrev_b32_e32 v50, 16, v10
	v_and_b32_e32 v51, 0xffff0000, v10
	v_lshlrev_b32_e32 v10, 16, v11
	v_and_b32_e32 v11, 0xffff0000, v11
	v_lshlrev_b32_e32 v52, 16, v12
	v_and_b32_e32 v53, 0xffff0000, v12
	v_lshlrev_b32_e32 v12, 16, v13
	v_and_b32_e32 v13, 0xffff0000, v13
	s_waitcnt lgkmcnt(0)
	v_lshlrev_b32_e32 v54, 16, v14
	v_and_b32_e32 v55, 0xffff0000, v14
	v_lshlrev_b32_e32 v14, 16, v15
	v_and_b32_e32 v15, 0xffff0000, v15
	v_lshlrev_b32_e32 v56, 16, v16
	v_and_b32_e32 v57, 0xffff0000, v16
	v_lshlrev_b32_e32 v16, 16, v17
	v_and_b32_e32 v17, 0xffff0000, v17
	s_waitcnt vmcnt(3)
	v_mov_b32_e32 v18, v94
	v_mov_b32_e32 v19, v95
	v_mov_b32_e32 v20, v96
	v_mov_b32_e32 v21, v97
	v_lshlrev_b32_e32 v58, 16, v18
	v_and_b32_e32 v59, 0xffff0000, v18
	v_lshlrev_b32_e32 v18, 16, v19
	v_and_b32_e32 v19, 0xffff0000, v19
	v_lshlrev_b32_e32 v60, 16, v20
	v_and_b32_e32 v61, 0xffff0000, v20
	v_lshlrev_b32_e32 v20, 16, v21
	v_and_b32_e32 v21, 0xffff0000, v21
	v_pk_fma_f32 v[42:43], v[58:59], s[38:39], v[42:43] op_sel_hi:[1,0,1]
	v_pk_fma_f32 v[18:19], v[18:19], s[38:39], v[2:3] op_sel_hi:[1,0,1]
	v_pk_fma_f32 v[44:45], v[60:61], s[38:39], v[44:45] op_sel_hi:[1,0,1]
	v_pk_fma_f32 v[20:21], v[20:21], s[38:39], v[4:5] op_sel_hi:[1,0,1]
	v_cvt_pk_bf16_f32 v2, v42, v43
	v_cvt_pk_bf16_f32 v3, v18, v19
	v_cvt_pk_bf16_f32 v4, v44, v45
	s_waitcnt vmcnt(2)
	v_mov_b32_e32 v22, v98
	v_mov_b32_e32 v23, v99
	v_mov_b32_e32 v24, v100
	v_mov_b32_e32 v25, v101
	v_lshlrev_b32_e32 v58, 16, v22
	v_and_b32_e32 v59, 0xffff0000, v22
	v_lshlrev_b32_e32 v22, 16, v23
	v_and_b32_e32 v23, 0xffff0000, v23
	v_lshlrev_b32_e32 v60, 16, v24
	v_and_b32_e32 v61, 0xffff0000, v24
	v_lshlrev_b32_e32 v24, 16, v25
	v_and_b32_e32 v25, 0xffff0000, v25
	s_waitcnt vmcnt(1)
	v_mov_b32_e32 v26, v102
	v_mov_b32_e32 v27, v103
	v_mov_b32_e32 v28, v104
	v_mov_b32_e32 v29, v105
	v_lshlrev_b32_e32 v62, 16, v26
	v_and_b32_e32 v63, 0xffff0000, v26
	v_lshlrev_b32_e32 v26, 16, v27
	v_and_b32_e32 v27, 0xffff0000, v27
	v_lshlrev_b32_e32 v64, 16, v28
	v_and_b32_e32 v65, 0xffff0000, v28
	v_lshlrev_b32_e32 v28, 16, v29
	v_and_b32_e32 v29, 0xffff0000, v29
	s_waitcnt vmcnt(0)
; DI unsigned pack2(float a, float b) { const f32x2 v = {a, b}; return __builtin_bit_cast(unsigned, __builtin_convertvector(v, bf16v2)); }
; template <int SWAP, int MODE>
; DI void epilogue8(const f32x4 (&acc)[2][2][4][2], char* lds, u16* __restrict__ dst, size_t ld, const u16* __restrict__ Hres) {
;     ...
; #pragma unroll 4
;   for (int i = 0; i < 16; ++i) {
;     const int q = tid + 512 * i, r = q >> 5, c8 = (q & 31) * 8;
;     uint4 v = *(const uint4*)(Ct + r * CT_LD + c8);
;     const size_t o = (size_t)r * ld + c8;
;     if (MODE == 1) {
;       const uint4 hv = *(const uint4*)(Hres + o);
;       float y[8], hx[8]; unpack8(v, y); unpack8(hv, hx);
;       v.x = pack2(ALPHA * hx[0] + y[0], ALPHA * hx[1] + y[1]); v.y = pack2(ALPHA * hx[2] + y[2], ALPHA * hx[3] + y[3]);
;       v.z = pack2(ALPHA * hx[4] + y[4], ALPHA * hx[5] + y[5]); v.w = pack2(ALPHA * hx[6] + y[6], ALPHA * hx[7] + y[7]);
;     }
;     *(uint4*)(dst + o) = v;
;   }
	v_mov_b32_e32 v30, v106
	v_mov_b32_e32 v31, v107
	v_mov_b32_e32 v32, v108
	v_mov_b32_e32 v33, v109
	v_lshlrev_b32_e32 v66, 16, v30
	v_and_b32_e32 v67, 0xffff0000, v30
	v_lshlrev_b32_e32 v30, 16, v31
	v_and_b32_e32 v31, 0xffff0000, v31
	v_lshlrev_b32_e32 v68, 16, v32
	v_and_b32_e32 v69, 0xffff0000, v32
	v_lshlrev_b32_e32 v32, 16, v33
	v_and_b32_e32 v33, 0xffff0000, v33
	v_cvt_pk_bf16_f32 v5, v20, v21
	v_pk_fma_f32 v[18:19], v[58:59], s[38:39], v[46:47] op_sel_hi:[1,0,1]
	v_pk_fma_f32 v[6:7], v[22:23], s[38:39], v[6:7] op_sel_hi:[1,0,1]
	v_pk_fma_f32 v[20:21], v[60:61], s[38:39], v[48:49] op_sel_hi:[1,0,1]
	v_pk_fma_f32 v[8:9], v[24:25], s[38:39], v[8:9] op_sel_hi:[1,0,1]
	v_pk_fma_f32 v[22:23], v[62:63], s[38:39], v[50:51] op_sel_hi:[1,0,1]
	v_pk_fma_f32 v[10:11], v[26:27], s[38:39], v[10:11] op_sel_hi:[1,0,1]
	v_pk_fma_f32 v[24:25], v[64:65], s[38:39], v[52:53] op_sel_hi:[1,0,1]
	v_pk_fma_f32 v[12:13], v[28:29], s[38:39], v[12:13] op_sel_hi:[1,0,1]
	v_pk_fma_f32 v[26:27], v[66:67], s[38:39], v[54:55] op_sel_hi:[1,0,1]
	v_pk_fma_f32 v[14:15], v[30:31], s[38:39], v[14:15] op_sel_hi:[1,0,1]
	v_pk_fma_f32 v[28:29], v[68:69], s[38:39], v[56:57] op_sel_hi:[1,0,1]
	v_pk_fma_f32 v[16:17], v[32:33], s[38:39], v[16:17] op_sel_hi:[1,0,1]
	v_add_u32_e32 v70, s16, v128
	v_ashrrev_i32_e32 v72, 5, v70
	v_add_u32_e32 v71, 0x200, v70
	v_ashrrev_i32_e32 v74, 5, v71
	v_add_u32_e32 v71, 0x400, v70
	v_ashrrev_i32_e32 v76, 5, v71
	v_add_u32_e32 v71, 0x600, v70
	v_ashrrev_i32_e32 v78, 5, v71
	v_ashrrev_i32_e32 v73, 31, v72
	v_lshlrev_b64 v[72:73], 11, v[72:73]
	v_or_b32_e32 v72, v72, v1
	v_lshl_add_u64 v[72:73], s[44:45], 0, v[72:73]
	v_ashrrev_i32_e32 v75, 31, v74
	v_lshlrev_b64 v[74:75], 11, v[74:75]
	v_or_b32_e32 v74, v74, v1
	v_lshl_add_u64 v[74:75], s[44:45], 0, v[74:75]
	v_ashrrev_i32_e32 v77, 31, v76
	v_lshlrev_b64 v[76:77], 11, v[76:77]
	v_or_b32_e32 v76, v76, v1
	v_lshl_add_u64 v[76:77], s[44:45], 0, v[76:77]
	v_ashrrev_i32_e32 v79, 31, v78
	v_lshlrev_b64 v[78:79], 11, v[78:79]
	v_or_b32_e32 v78, v78, v1
	v_lshl_add_u64 v[78:79], s[44:45], 0, v[78:79]
	global_load_dwordx4 v[110:113], v[72:73], off
	global_load_dwordx4 v[114:117], v[74:75], off
	global_load_dwordx4 v[118:121], v[76:77], off
	global_load_dwordx4 v[122:125], v[78:79], off
	global_store_dwordx4 v[34:35], v[2:5], off
	s_nop 1
	v_cvt_pk_bf16_f32 v2, v18, v19
	v_cvt_pk_bf16_f32 v3, v6, v7
	v_cvt_pk_bf16_f32 v4, v20, v21
	v_cvt_pk_bf16_f32 v5, v8, v9
	v_cvt_pk_bf16_f32 v6, v22, v23
	v_cvt_pk_bf16_f32 v7, v10, v11
	v_cvt_pk_bf16_f32 v8, v24, v25
	v_cvt_pk_bf16_f32 v9, v12, v13
	v_cvt_pk_bf16_f32 v10, v26, v27
	v_cvt_pk_bf16_f32 v11, v14, v15
	v_cvt_pk_bf16_f32 v12, v28, v29
	v_cvt_pk_bf16_f32 v13, v16, v17
	global_store_dwordx4 v[36:37], v[2:5], off
	global_store_dwordx4 v[38:39], v[6:9], off
	global_store_dwordx4 v[40:41], v[10:13], off
	v_add_u32_e32 v2, s16, v128
	v_ashrrev_i32_e32 v6, 5, v2
	v_add_u32_e32 v4, 0x200, v2
	v_add_u32_e32 v5, 0x400, v2
	v_add_u32_e32 v8, 0x600, v2
	v_ashrrev_i32_e32 v7, 31, v6
	v_ashrrev_i32_e32 v10, 5, v4
	v_ashrrev_i32_e32 v14, 5, v5
	v_ashrrev_i32_e32 v18, 5, v8
	v_lshlrev_b64 v[20:21], 11, v[6:7]
	v_ashrrev_i32_e32 v11, 31, v10
	v_ashrrev_i32_e32 v15, 31, v14
	v_ashrrev_i32_e32 v19, 31, v18
	v_or_b32_e32 v20, v20, v1
	v_mad_u64_u32 v[16:17], s[22:23], v18, s50, v[0:1]
	v_lshlrev_b64 v[22:23], 11, v[10:11]
	v_lshlrev_b64 v[24:25], 11, v[14:15]
	v_lshlrev_b64 v[26:27], 11, v[18:19]
	v_lshl_add_u64 v[18:19], s[44:45], 0, v[20:21]
	v_lshl_add_u64 v[34:35], s[42:43], 0, v[20:21]
	v_or_b32_e32 v22, v22, v1
	v_or_b32_e32 v24, v24, v1
	v_or_b32_e32 v26, v26, v1
	v_mad_u64_u32 v[2:3], s[22:23], v6, s50, v[0:1]
	v_mad_u64_u32 v[6:7], s[22:23], v10, s50, v[0:1]
	v_mad_u64_u32 v[12:13], s[22:23], v14, s50, v[0:1]
	v_lshl_add_u64 v[28:29], s[44:45], 0, v[22:23]
	v_lshl_add_u64 v[30:31], s[44:45], 0, v[24:25]
	v_lshl_add_u64 v[32:33], s[44:45], 0, v[26:27]
	ds_read_b128 v[2:5], v2
	ds_read_b128 v[6:9], v6
	ds_read_b128 v[10:13], v12
	ds_read_b128 v[14:17], v16
	v_lshl_add_u64 v[36:37], s[42:43], 0, v[22:23]
	v_lshl_add_u64 v[38:39], s[42:43], 0, v[24:25]
	v_lshl_add_u64 v[40:41], s[42:43], 0, v[26:27]
	s_nop 0
	s_nop 0
	s_waitcnt lgkmcnt(3)
	v_lshlrev_b32_e32 v42, 16, v2
	v_and_b32_e32 v43, 0xffff0000, v2
	v_lshlrev_b32_e32 v2, 16, v3
	v_and_b32_e32 v3, 0xffff0000, v3
	v_lshlrev_b32_e32 v44, 16, v4
	v_and_b32_e32 v45, 0xffff0000, v4
	v_lshlrev_b32_e32 v4, 16, v5
	v_and_b32_e32 v5, 0xffff0000, v5
	s_waitcnt lgkmcnt(2)
	v_lshlrev_b32_e32 v46, 16, v6
	v_and_b32_e32 v47, 0xffff0000, v6
	v_lshlrev_b32_e32 v6, 16, v7
	v_and_b32_e32 v7, 0xffff0000, v7
	v_lshlrev_b32_e32 v48, 16, v8
	v_and_b32_e32 v49, 0xffff0000, v8
	v_lshlrev_b32_e32 v8, 16, v9
	v_and_b32_e32 v9, 0xffff0000, v9
	s_addk_i32 s16, 0x800
	s_waitcnt lgkmcnt(1)
	v_lshlrev_b32_e32 v50, 16, v10
	v_and_b32_e32 v51, 0xffff0000, v10
	v_lshlrev_b32_e32 v10, 16, v11
	v_and_b32_e32 v11, 0xffff0000, v11
	v_lshlrev_b32_e32 v52, 16, v12
	v_and_b32_e32 v53, 0xffff0000, v12
	v_lshlrev_b32_e32 v12, 16, v13
	v_and_b32_e32 v13, 0xffff0000, v13
	s_waitcnt lgkmcnt(0)
	v_lshlrev_b32_e32 v54, 16, v14
	v_and_b32_e32 v55, 0xffff0000, v14
	v_lshlrev_b32_e32 v14, 16, v15
	v_and_b32_e32 v15, 0xffff0000, v15
	v_lshlrev_b32_e32 v56, 16, v16
	v_and_b32_e32 v57, 0xffff0000, v16
	v_lshlrev_b32_e32 v16, 16, v17
	v_and_b32_e32 v17, 0xffff0000, v17
	s_waitcnt vmcnt(7)
; DI unsigned pack2(float a, float b) { const f32x2 v = {a, b}; return __builtin_bit_cast(unsigned, __builtin_convertvector(v, bf16v2)); }
; template <int SWAP, int MODE>
; DI void epilogue8(const f32x4 (&acc)[2][2][4][2], char* lds, u16* __restrict__ dst, size_t ld, const u16* __restrict__ Hres) {
;     ...
; #pragma unroll 4
;   for (int i = 0; i < 16; ++i) {
;     const int q = tid + 512 * i, r = q >> 5, c8 = (q & 31) * 8;
;     uint4 v = *(const uint4*)(Ct + r * CT_LD + c8);
;     const size_t o = (size_t)r * ld + c8;
;     if (MODE == 1) {
;       const uint4 hv = *(const uint4*)(Hres + o);
;       float y[8], hx[8]; unpack8(v, y); unpack8(hv, hx);
;       v.x = pack2(ALPHA * hx[0] + y[0], ALPHA * hx[1] + y[1]); v.y = pack2(ALPHA * hx[2] + y[2], ALPHA * hx[3] + y[3]);
;       v.z = pack2(ALPHA * hx[4] + y[4], ALPHA * hx[5] + y[5]); v.w = pack2(ALPHA * hx[6] + y[6], ALPHA * hx[7] + y[7]);
;     }
;     *(uint4*)(dst + o) = v;
;   }
	v_mov_b32_e32 v18, v110
	v_mov_b32_e32 v19, v111
	v_mov_b32_e32 v20, v112
	v_mov_b32_e32 v21, v113
	v_lshlrev_b32_e32 v58, 16, v18
	v_and_b32_e32 v59, 0xffff0000, v18
	v_lshlrev_b32_e32 v18, 16, v19
	v_and_b32_e32 v19, 0xffff0000, v19
	v_lshlrev_b32_e32 v60, 16, v20
	v_and_b32_e32 v61, 0xffff0000, v20
	v_lshlrev_b32_e32 v20, 16, v21
	v_and_b32_e32 v21, 0xffff0000, v21
	v_pk_fma_f32 v[42:43], v[58:59], s[38:39], v[42:43] op_sel_hi:[1,0,1]
	v_pk_fma_f32 v[18:19], v[18:19], s[38:39], v[2:3] op_sel_hi:[1,0,1]
	v_pk_fma_f32 v[44:45], v[60:61], s[38:39], v[44:45] op_sel_hi:[1,0,1]
	v_pk_fma_f32 v[20:21], v[20:21], s[38:39], v[4:5] op_sel_hi:[1,0,1]
	v_cvt_pk_bf16_f32 v2, v42, v43
	v_cvt_pk_bf16_f32 v3, v18, v19
	v_cvt_pk_bf16_f32 v4, v44, v45
	s_waitcnt vmcnt(6)
	v_mov_b32_e32 v22, v114
	v_mov_b32_e32 v23, v115
	v_mov_b32_e32 v24, v116
	v_mov_b32_e32 v25, v117
	v_lshlrev_b32_e32 v58, 16, v22
	v_and_b32_e32 v59, 0xffff0000, v22
	v_lshlrev_b32_e32 v22, 16, v23
	v_and_b32_e32 v23, 0xffff0000, v23
	v_lshlrev_b32_e32 v60, 16, v24
	v_and_b32_e32 v61, 0xffff0000, v24
	v_lshlrev_b32_e32 v24, 16, v25
	v_and_b32_e32 v25, 0xffff0000, v25
	s_waitcnt vmcnt(5)
	v_mov_b32_e32 v26, v118
	v_mov_b32_e32 v27, v119
	v_mov_b32_e32 v28, v120
	v_mov_b32_e32 v29, v121
	v_lshlrev_b32_e32 v62, 16, v26
	v_and_b32_e32 v63, 0xffff0000, v26
	v_lshlrev_b32_e32 v26, 16, v27
	v_and_b32_e32 v27, 0xffff0000, v27
	v_lshlrev_b32_e32 v64, 16, v28
	v_and_b32_e32 v65, 0xffff0000, v28
	v_lshlrev_b32_e32 v28, 16, v29
	v_and_b32_e32 v29, 0xffff0000, v29
	s_waitcnt vmcnt(4)
	v_mov_b32_e32 v30, v122
	v_mov_b32_e32 v31, v123
	v_mov_b32_e32 v32, v124
	v_mov_b32_e32 v33, v125
	v_lshlrev_b32_e32 v66, 16, v30
	v_and_b32_e32 v67, 0xffff0000, v30
	v_lshlrev_b32_e32 v30, 16, v31
	v_and_b32_e32 v31, 0xffff0000, v31
	v_lshlrev_b32_e32 v68, 16, v32
	v_and_b32_e32 v69, 0xffff0000, v32
	v_lshlrev_b32_e32 v32, 16, v33
	v_and_b32_e32 v33, 0xffff0000, v33
	v_cvt_pk_bf16_f32 v5, v20, v21
	v_pk_fma_f32 v[18:19], v[58:59], s[38:39], v[46:47] op_sel_hi:[1,0,1]
	v_pk_fma_f32 v[6:7], v[22:23], s[38:39], v[6:7] op_sel_hi:[1,0,1]
	v_pk_fma_f32 v[20:21], v[60:61], s[38:39], v[48:49] op_sel_hi:[1,0,1]
	v_pk_fma_f32 v[8:9], v[24:25], s[38:39], v[8:9] op_sel_hi:[1,0,1]
	v_pk_fma_f32 v[22:23], v[62:63], s[38:39], v[50:51] op_sel_hi:[1,0,1]
	v_pk_fma_f32 v[10:11], v[26:27], s[38:39], v[10:11] op_sel_hi:[1,0,1]
	v_pk_fma_f32 v[24:25], v[64:65], s[38:39], v[52:53] op_sel_hi:[1,0,1]
	v_pk_fma_f32 v[12:13], v[28:29], s[38:39], v[12:13] op_sel_hi:[1,0,1]
	v_pk_fma_f32 v[26:27], v[66:67], s[38:39], v[54:55] op_sel_hi:[1,0,1]
	v_pk_fma_f32 v[14:15], v[30:31], s[38:39], v[14:15] op_sel_hi:[1,0,1]
	v_pk_fma_f32 v[28:29], v[68:69], s[38:39], v[56:57] op_sel_hi:[1,0,1]
	v_pk_fma_f32 v[16:17], v[32:33], s[38:39], v[16:17] op_sel_hi:[1,0,1]
	v_add_u32_e32 v70, s16, v128
	v_ashrrev_i32_e32 v72, 5, v70
	v_add_u32_e32 v71, 0x200, v70
	v_ashrrev_i32_e32 v74, 5, v71
	v_add_u32_e32 v71, 0x400, v70
	v_ashrrev_i32_e32 v76, 5, v71
	v_add_u32_e32 v71, 0x600, v70
	v_ashrrev_i32_e32 v78, 5, v71
	v_ashrrev_i32_e32 v73, 31, v72
	v_lshlrev_b64 v[72:73], 11, v[72:73]
	v_or_b32_e32 v72, v72, v1
	v_lshl_add_u64 v[72:73], s[44:45], 0, v[72:73]
	v_ashrrev_i32_e32 v75, 31, v74
	v_lshlrev_b64 v[74:75], 11, v[74:75]
	v_or_b32_e32 v74, v74, v1
	v_lshl_add_u64 v[74:75], s[44:45], 0, v[74:75]
	v_ashrrev_i32_e32 v77, 31, v76
	v_lshlrev_b64 v[76:77], 11, v[76:77]
	v_or_b32_e32 v76, v76, v1
	v_lshl_add_u64 v[76:77], s[44:45], 0, v[76:77]
	v_ashrrev_i32_e32 v79, 31, v78
	v_lshlrev_b64 v[78:79], 11, v[78:79]
	v_or_b32_e32 v78, v78, v1
	v_lshl_add_u64 v[78:79], s[44:45], 0, v[78:79]
	global_load_dwordx4 v[94:97], v[72:73], off
	global_load_dwordx4 v[98:101], v[74:75], off
	global_load_dwordx4 v[102:105], v[76:77], off
	global_load_dwordx4 v[106:109], v[78:79], off
	global_store_dwordx4 v[34:35], v[2:5], off
	s_nop 1
	v_cvt_pk_bf16_f32 v2, v18, v19
	v_cvt_pk_bf16_f32 v3, v6, v7
	v_cvt_pk_bf16_f32 v4, v20, v21
	v_cvt_pk_bf16_f32 v5, v8, v9
	v_cvt_pk_bf16_f32 v6, v22, v23
	v_cvt_pk_bf16_f32 v7, v10, v11
	v_cvt_pk_bf16_f32 v8, v24, v25
	v_cvt_pk_bf16_f32 v9, v12, v13
	v_cvt_pk_bf16_f32 v10, v26, v27
	v_cvt_pk_bf16_f32 v11, v14, v15
	v_cvt_pk_bf16_f32 v12, v28, v29
	v_cvt_pk_bf16_f32 v13, v16, v17
	global_store_dwordx4 v[36:37], v[2:5], off
	global_store_dwordx4 v[38:39], v[6:9], off
	global_store_dwordx4 v[40:41], v[10:13], off
	v_add_u32_e32 v2, s16, v128
	v_ashrrev_i32_e32 v6, 5, v2
	v_add_u32_e32 v4, 0x200, v2
	v_add_u32_e32 v5, 0x400, v2
	v_add_u32_e32 v8, 0x600, v2
	v_ashrrev_i32_e32 v7, 31, v6
	v_ashrrev_i32_e32 v10, 5, v4
	v_ashrrev_i32_e32 v14, 5, v5
	v_ashrrev_i32_e32 v18, 5, v8
	v_lshlrev_b64 v[20:21], 11, v[6:7]
	v_ashrrev_i32_e32 v11, 31, v10
	v_ashrrev_i32_e32 v15, 31, v14
	v_ashrrev_i32_e32 v19, 31, v18
	v_or_b32_e32 v20, v20, v1
	v_mad_u64_u32 v[16:17], s[22:23], v18, s50, v[0:1]
	v_lshlrev_b64 v[22:23], 11, v[10:11]
	v_lshlrev_b64 v[24:25], 11, v[14:15]
	v_lshlrev_b64 v[26:27], 11, v[18:19]
	v_lshl_add_u64 v[18:19], s[44:45], 0, v[20:21]
	v_lshl_add_u64 v[34:35], s[42:43], 0, v[20:21]
	v_or_b32_e32 v22, v22, v1
	v_or_b32_e32 v24, v24, v1
	v_or_b32_e32 v26, v26, v1
	v_mad_u64_u32 v[2:3], s[22:23], v6, s50, v[0:1]
	v_mad_u64_u32 v[6:7], s[22:23], v10, s50, v[0:1]
	v_mad_u64_u32 v[12:13], s[22:23], v14, s50, v[0:1]
	v_lshl_add_u64 v[28:29], s[44:45], 0, v[22:23]
	v_lshl_add_u64 v[30:31], s[44:45], 0, v[24:25]
	v_lshl_add_u64 v[32:33], s[44:45], 0, v[26:27]
	ds_read_b128 v[2:5], v2
	ds_read_b128 v[6:9], v6
	ds_read_b128 v[10:13], v12
	ds_read_b128 v[14:17], v16
	v_lshl_add_u64 v[36:37], s[42:43], 0, v[22:23]
	v_lshl_add_u64 v[38:39], s[42:43], 0, v[24:25]
	v_lshl_add_u64 v[40:41], s[42:43], 0, v[26:27]
	s_nop 0
	s_nop 0
	s_waitcnt lgkmcnt(3)
; DI unsigned pack2(float a, float b) { const f32x2 v = {a, b}; return __builtin_bit_cast(unsigned, __builtin_convertvector(v, bf16v2)); }
; template <int SWAP, int MODE>
; DI void epilogue8(const f32x4 (&acc)[2][2][4][2], char* lds, u16* __restrict__ dst, size_t ld, const u16* __restrict__ Hres) {
;     ...
; #pragma unroll 4
;   for (int i = 0; i < 16; ++i) {
;     const int q = tid + 512 * i, r = q >> 5, c8 = (q & 31) * 8;
;     uint4 v = *(const uint4*)(Ct + r * CT_LD + c8);
;     const size_t o = (size_t)r * ld + c8;
;     if (MODE == 1) {
;       const uint4 hv = *(const uint4*)(Hres + o);
;       float y[8], hx[8]; unpack8(v, y); unpack8(hv, hx);
;       v.x = pack2(ALPHA * hx[0] + y[0], ALPHA * hx[1] + y[1]); v.y = pack2(ALPHA * hx[2] + y[2], ALPHA * hx[3] + y[3]);
;       v.z = pack2(ALPHA * hx[4] + y[4], ALPHA * hx[5] + y[5]); v.w = pack2(ALPHA * hx[6] + y[6], ALPHA * hx[7] + y[7]);
;     }
;     *(uint4*)(dst + o) = v;
;   }
	v_lshlrev_b32_e32 v42, 16, v2
	v_and_b32_e32 v43, 0xffff0000, v2
	v_lshlrev_b32_e32 v2, 16, v3
	v_and_b32_e32 v3, 0xffff0000, v3
	v_lshlrev_b32_e32 v44, 16, v4
	v_and_b32_e32 v45, 0xffff0000, v4
	v_lshlrev_b32_e32 v4, 16, v5
	v_and_b32_e32 v5, 0xffff0000, v5
	s_waitcnt lgkmcnt(2)
	v_lshlrev_b32_e32 v46, 16, v6
	v_and_b32_e32 v47, 0xffff0000, v6
	v_lshlrev_b32_e32 v6, 16, v7
	v_and_b32_e32 v7, 0xffff0000, v7
	v_lshlrev_b32_e32 v48, 16, v8
	v_and_b32_e32 v49, 0xffff0000, v8
	v_lshlrev_b32_e32 v8, 16, v9
	v_and_b32_e32 v9, 0xffff0000, v9
	s_addk_i32 s16, 0x800
	s_waitcnt lgkmcnt(1)
	v_lshlrev_b32_e32 v50, 16, v10
	v_and_b32_e32 v51, 0xffff0000, v10
	v_lshlrev_b32_e32 v10, 16, v11
	v_and_b32_e32 v11, 0xffff0000, v11
	v_lshlrev_b32_e32 v52, 16, v12
	v_and_b32_e32 v53, 0xffff0000, v12
	v_lshlrev_b32_e32 v12, 16, v13
	v_and_b32_e32 v13, 0xffff0000, v13
	s_waitcnt lgkmcnt(0)
	v_lshlrev_b32_e32 v54, 16, v14
	v_and_b32_e32 v55, 0xffff0000, v14
	v_lshlrev_b32_e32 v14, 16, v15
	v_and_b32_e32 v15, 0xffff0000, v15
	v_lshlrev_b32_e32 v56, 16, v16
	v_and_b32_e32 v57, 0xffff0000, v16
	v_lshlrev_b32_e32 v16, 16, v17
	v_and_b32_e32 v17, 0xffff0000, v17
	s_waitcnt vmcnt(7)
	v_mov_b32_e32 v18, v94
	v_mov_b32_e32 v19, v95
	v_mov_b32_e32 v20, v96
	v_mov_b32_e32 v21, v97
	v_lshlrev_b32_e32 v58, 16, v18
	v_and_b32_e32 v59, 0xffff0000, v18
	v_lshlrev_b32_e32 v18, 16, v19
	v_and_b32_e32 v19, 0xffff0000, v19
	v_lshlrev_b32_e32 v60, 16, v20
	v_and_b32_e32 v61, 0xffff0000, v20
	v_lshlrev_b32_e32 v20, 16, v21
	v_and_b32_e32 v21, 0xffff0000, v21
	v_pk_fma_f32 v[42:43], v[58:59], s[38:39], v[42:43] op_sel_hi:[1,0,1]
	v_pk_fma_f32 v[18:19], v[18:19], s[38:39], v[2:3] op_sel_hi:[1,0,1]
	v_pk_fma_f32 v[44:45], v[60:61], s[38:39], v[44:45] op_sel_hi:[1,0,1]
	v_pk_fma_f32 v[20:21], v[20:21], s[38:39], v[4:5] op_sel_hi:[1,0,1]
	v_cvt_pk_bf16_f32 v2, v42, v43
	v_cvt_pk_bf16_f32 v3, v18, v19
	v_cvt_pk_bf16_f32 v4, v44, v45
	s_waitcnt vmcnt(6)
	v_mov_b32_e32 v22, v98
	v_mov_b32_e32 v23, v99
	v_mov_b32_e32 v24, v100
	v_mov_b32_e32 v25, v101
	v_lshlrev_b32_e32 v58, 16, v22
	v_and_b32_e32 v59, 0xffff0000, v22
	v_lshlrev_b32_e32 v22, 16, v23
	v_and_b32_e32 v23, 0xffff0000, v23
	v_lshlrev_b32_e32 v60, 16, v24
	v_and_b32_e32 v61, 0xffff0000, v24
	v_lshlrev_b32_e32 v24, 16, v25
	v_and_b32_e32 v25, 0xffff0000, v25
	s_waitcnt vmcnt(5)
	v_mov_b32_e32 v26, v102
	v_mov_b32_e32 v27, v103
	v_mov_b32_e32 v28, v104
	v_mov_b32_e32 v29, v105
	v_lshlrev_b32_e32 v62, 16, v26
	v_and_b32_e32 v63, 0xffff0000, v26
	v_lshlrev_b32_e32 v26, 16, v27
	v_and_b32_e32 v27, 0xffff0000, v27
	v_lshlrev_b32_e32 v64, 16, v28
	v_and_b32_e32 v65, 0xffff0000, v28
	v_lshlrev_b32_e32 v28, 16, v29
	v_and_b32_e32 v29, 0xffff0000, v29
	s_waitcnt vmcnt(4)
	v_mov_b32_e32 v30, v106
	v_mov_b32_e32 v31, v107
	v_mov_b32_e32 v32, v108
	v_mov_b32_e32 v33, v109
	v_lshlrev_b32_e32 v66, 16, v30
	v_and_b32_e32 v67, 0xffff0000, v30
	v_lshlrev_b32_e32 v30, 16, v31
	v_and_b32_e32 v31, 0xffff0000, v31
	v_lshlrev_b32_e32 v68, 16, v32
	v_and_b32_e32 v69, 0xffff0000, v32
	v_lshlrev_b32_e32 v32, 16, v33
	v_and_b32_e32 v33, 0xffff0000, v33
	v_cvt_pk_bf16_f32 v5, v20, v21
	v_pk_fma_f32 v[18:19], v[58:59], s[38:39], v[46:47] op_sel_hi:[1,0,1]
	v_pk_fma_f32 v[6:7], v[22:23], s[38:39], v[6:7] op_sel_hi:[1,0,1]
	v_pk_fma_f32 v[20:21], v[60:61], s[38:39], v[48:49] op_sel_hi:[1,0,1]
	v_pk_fma_f32 v[8:9], v[24:25], s[38:39], v[8:9] op_sel_hi:[1,0,1]
	v_pk_fma_f32 v[22:23], v[62:63], s[38:39], v[50:51] op_sel_hi:[1,0,1]
	v_pk_fma_f32 v[10:11], v[26:27], s[38:39], v[10:11] op_sel_hi:[1,0,1]
	v_pk_fma_f32 v[24:25], v[64:65], s[38:39], v[52:53] op_sel_hi:[1,0,1]
	v_pk_fma_f32 v[12:13], v[28:29], s[38:39], v[12:13] op_sel_hi:[1,0,1]
	v_pk_fma_f32 v[26:27], v[66:67], s[38:39], v[54:55] op_sel_hi:[1,0,1]
	v_pk_fma_f32 v[14:15], v[30:31], s[38:39], v[14:15] op_sel_hi:[1,0,1]
	v_pk_fma_f32 v[28:29], v[68:69], s[38:39], v[56:57] op_sel_hi:[1,0,1]
	v_pk_fma_f32 v[16:17], v[32:33], s[38:39], v[16:17] op_sel_hi:[1,0,1]
	v_add_u32_e32 v70, s16, v128
	v_ashrrev_i32_e32 v72, 5, v70
	v_add_u32_e32 v71, 0x200, v70
	v_ashrrev_i32_e32 v74, 5, v71
	v_add_u32_e32 v71, 0x400, v70
	v_ashrrev_i32_e32 v76, 5, v71
	v_add_u32_e32 v71, 0x600, v70
	v_ashrrev_i32_e32 v78, 5, v71
	v_ashrrev_i32_e32 v73, 31, v72
	v_lshlrev_b64 v[72:73], 11, v[72:73]
	v_or_b32_e32 v72, v72, v1
	v_lshl_add_u64 v[72:73], s[44:45], 0, v[72:73]
	v_ashrrev_i32_e32 v75, 31, v74
	v_lshlrev_b64 v[74:75], 11, v[74:75]
	v_or_b32_e32 v74, v74, v1
	v_lshl_add_u64 v[74:75], s[44:45], 0, v[74:75]
	v_ashrrev_i32_e32 v77, 31, v76
	v_lshlrev_b64 v[76:77], 11, v[76:77]
	v_or_b32_e32 v76, v76, v1
	v_lshl_add_u64 v[76:77], s[44:45], 0, v[76:77]
	v_ashrrev_i32_e32 v79, 31, v78
	v_lshlrev_b64 v[78:79], 11, v[78:79]
	v_or_b32_e32 v78, v78, v1
	v_lshl_add_u64 v[78:79], s[44:45], 0, v[78:79]
	global_load_dwordx4 v[110:113], v[72:73], off
	global_load_dwordx4 v[114:117], v[74:75], off
	global_load_dwordx4 v[118:121], v[76:77], off
	global_load_dwordx4 v[122:125], v[78:79], off
	global_store_dwordx4 v[34:35], v[2:5], off
	s_nop 1
	v_cvt_pk_bf16_f32 v2, v18, v19
	v_cvt_pk_bf16_f32 v3, v6, v7
	v_cvt_pk_bf16_f32 v4, v20, v21
	v_cvt_pk_bf16_f32 v5, v8, v9
	v_cvt_pk_bf16_f32 v6, v22, v23
	v_cvt_pk_bf16_f32 v7, v10, v11
	v_cvt_pk_bf16_f32 v8, v24, v25
	v_cvt_pk_bf16_f32 v9, v12, v13
	v_cvt_pk_bf16_f32 v10, v26, v27
	v_cvt_pk_bf16_f32 v11, v14, v15
	v_cvt_pk_bf16_f32 v12, v28, v29
	v_cvt_pk_bf16_f32 v13, v16, v17
	global_store_dwordx4 v[36:37], v[2:5], off
	global_store_dwordx4 v[38:39], v[6:9], off
	global_store_dwordx4 v[40:41], v[10:13], off
	v_add_u32_e32 v2, s16, v128
	v_ashrrev_i32_e32 v6, 5, v2
	v_add_u32_e32 v4, 0x200, v2
	v_add_u32_e32 v5, 0x400, v2
	v_add_u32_e32 v8, 0x600, v2
	v_ashrrev_i32_e32 v7, 31, v6
	v_ashrrev_i32_e32 v10, 5, v4
	v_ashrrev_i32_e32 v14, 5, v5
	v_ashrrev_i32_e32 v18, 5, v8
	v_lshlrev_b64 v[20:21], 11, v[6:7]
	v_ashrrev_i32_e32 v11, 31, v10
	v_ashrrev_i32_e32 v15, 31, v14
	v_ashrrev_i32_e32 v19, 31, v18
	v_or_b32_e32 v20, v20, v1
	v_mad_u64_u32 v[16:17], s[22:23], v18, s50, v[0:1]
	v_lshlrev_b64 v[22:23], 11, v[10:11]
	v_lshlrev_b64 v[24:25], 11, v[14:15]
	v_lshlrev_b64 v[26:27], 11, v[18:19]
	v_lshl_add_u64 v[18:19], s[44:45], 0, v[20:21]
	v_lshl_add_u64 v[34:35], s[42:43], 0, v[20:21]
	v_or_b32_e32 v22, v22, v1
	v_or_b32_e32 v24, v24, v1
	v_or_b32_e32 v26, v26, v1
	v_mad_u64_u32 v[2:3], s[22:23], v6, s50, v[0:1]
	v_mad_u64_u32 v[6:7], s[22:23], v10, s50, v[0:1]
	v_mad_u64_u32 v[12:13], s[22:23], v14, s50, v[0:1]
	v_lshl_add_u64 v[28:29], s[44:45], 0, v[22:23]
	v_lshl_add_u64 v[30:31], s[44:45], 0, v[24:25]
	v_lshl_add_u64 v[32:33], s[44:45], 0, v[26:27]
	ds_read_b128 v[2:5], v2
	ds_read_b128 v[6:9], v6
	ds_read_b128 v[10:13], v12
	ds_read_b128 v[14:17], v16
	v_lshl_add_u64 v[36:37], s[42:43], 0, v[22:23]
	v_lshl_add_u64 v[38:39], s[42:43], 0, v[24:25]
	v_lshl_add_u64 v[40:41], s[42:43], 0, v[26:27]
	s_nop 0
	s_nop 0
	s_waitcnt lgkmcnt(3)
; DI unsigned pack2(float a, float b) { const f32x2 v = {a, b}; return __builtin_bit_cast(unsigned, __builtin_convertvector(v, bf16v2)); }
; template <int SWAP, int MODE>
; DI void epilogue8(const f32x4 (&acc)[2][2][4][2], char* lds, u16* __restrict__ dst, size_t ld, const u16* __restrict__ Hres) {
;     ...
; #pragma unroll 4
;   for (int i = 0; i < 16; ++i) {
;     const int q = tid + 512 * i, r = q >> 5, c8 = (q & 31) * 8;
;     uint4 v = *(const uint4*)(Ct + r * CT_LD + c8);
;     const size_t o = (size_t)r * ld + c8;
;     if (MODE == 1) {
;       const uint4 hv = *(const uint4*)(Hres + o);
;       float y[8], hx[8]; unpack8(v, y); unpack8(hv, hx);
;       v.x = pack2(ALPHA * hx[0] + y[0], ALPHA * hx[1] + y[1]); v.y = pack2(ALPHA * hx[2] + y[2], ALPHA * hx[3] + y[3]);
;       v.z = pack2(ALPHA * hx[4] + y[4], ALPHA * hx[5] + y[5]); v.w = pack2(ALPHA * hx[6] + y[6], ALPHA * hx[7] + y[7]);
;     }
;     *(uint4*)(dst + o) = v;
;   }
;   __syncthreads();
	v_lshlrev_b32_e32 v42, 16, v2
	v_and_b32_e32 v43, 0xffff0000, v2
	v_lshlrev_b32_e32 v2, 16, v3
	v_and_b32_e32 v3, 0xffff0000, v3
	v_lshlrev_b32_e32 v44, 16, v4
	v_and_b32_e32 v45, 0xffff0000, v4
	v_lshlrev_b32_e32 v4, 16, v5
	v_and_b32_e32 v5, 0xffff0000, v5
	s_waitcnt lgkmcnt(2)
	v_lshlrev_b32_e32 v46, 16, v6
	v_and_b32_e32 v47, 0xffff0000, v6
	v_lshlrev_b32_e32 v6, 16, v7
	v_and_b32_e32 v7, 0xffff0000, v7
	v_lshlrev_b32_e32 v48, 16, v8
	v_and_b32_e32 v49, 0xffff0000, v8
	v_lshlrev_b32_e32 v8, 16, v9
	v_and_b32_e32 v9, 0xffff0000, v9
	s_addk_i32 s16, 0x800
	s_waitcnt lgkmcnt(1)
	v_lshlrev_b32_e32 v50, 16, v10
	v_and_b32_e32 v51, 0xffff0000, v10
	v_lshlrev_b32_e32 v10, 16, v11
	v_and_b32_e32 v11, 0xffff0000, v11
	v_lshlrev_b32_e32 v52, 16, v12
	v_and_b32_e32 v53, 0xffff0000, v12
	v_lshlrev_b32_e32 v12, 16, v13
	v_and_b32_e32 v13, 0xffff0000, v13
	s_waitcnt lgkmcnt(0)
	v_lshlrev_b32_e32 v54, 16, v14
	v_and_b32_e32 v55, 0xffff0000, v14
	v_lshlrev_b32_e32 v14, 16, v15
	v_and_b32_e32 v15, 0xffff0000, v15
	v_lshlrev_b32_e32 v56, 16, v16
	v_and_b32_e32 v57, 0xffff0000, v16
	v_lshlrev_b32_e32 v16, 16, v17
	v_and_b32_e32 v17, 0xffff0000, v17
	s_waitcnt vmcnt(7)
	v_mov_b32_e32 v18, v110
	v_mov_b32_e32 v19, v111
	v_mov_b32_e32 v20, v112
	v_mov_b32_e32 v21, v113
	v_lshlrev_b32_e32 v58, 16, v18
	v_and_b32_e32 v59, 0xffff0000, v18
	v_lshlrev_b32_e32 v18, 16, v19
	v_and_b32_e32 v19, 0xffff0000, v19
	v_lshlrev_b32_e32 v60, 16, v20
	v_and_b32_e32 v61, 0xffff0000, v20
	v_lshlrev_b32_e32 v20, 16, v21
	v_and_b32_e32 v21, 0xffff0000, v21
	v_pk_fma_f32 v[42:43], v[58:59], s[38:39], v[42:43] op_sel_hi:[1,0,1]
	v_pk_fma_f32 v[18:19], v[18:19], s[38:39], v[2:3] op_sel_hi:[1,0,1]
	v_pk_fma_f32 v[44:45], v[60:61], s[38:39], v[44:45] op_sel_hi:[1,0,1]
	v_pk_fma_f32 v[20:21], v[20:21], s[38:39], v[4:5] op_sel_hi:[1,0,1]
	v_cvt_pk_bf16_f32 v2, v42, v43
	v_cvt_pk_bf16_f32 v3, v18, v19
	v_cvt_pk_bf16_f32 v4, v44, v45
	s_waitcnt vmcnt(6)
	v_mov_b32_e32 v22, v114
	v_mov_b32_e32 v23, v115
	v_mov_b32_e32 v24, v116
	v_mov_b32_e32 v25, v117
	v_lshlrev_b32_e32 v58, 16, v22
	v_and_b32_e32 v59, 0xffff0000, v22
	v_lshlrev_b32_e32 v22, 16, v23
	v_and_b32_e32 v23, 0xffff0000, v23
	v_lshlrev_b32_e32 v60, 16, v24
	v_and_b32_e32 v61, 0xffff0000, v24
	v_lshlrev_b32_e32 v24, 16, v25
	v_and_b32_e32 v25, 0xffff0000, v25
	s_waitcnt vmcnt(5)
	v_mov_b32_e32 v26, v118
	v_mov_b32_e32 v27, v119
	v_mov_b32_e32 v28, v120
	v_mov_b32_e32 v29, v121
	v_lshlrev_b32_e32 v62, 16, v26
	v_and_b32_e32 v63, 0xffff0000, v26
	v_lshlrev_b32_e32 v26, 16, v27
	v_and_b32_e32 v27, 0xffff0000, v27
	v_lshlrev_b32_e32 v64, 16, v28
	v_and_b32_e32 v65, 0xffff0000, v28
	v_lshlrev_b32_e32 v28, 16, v29
	v_and_b32_e32 v29, 0xffff0000, v29
	s_waitcnt vmcnt(4)
	v_mov_b32_e32 v30, v122
	v_mov_b32_e32 v31, v123
	v_mov_b32_e32 v32, v124
	v_mov_b32_e32 v33, v125
	v_lshlrev_b32_e32 v66, 16, v30
	v_and_b32_e32 v67, 0xffff0000, v30
	v_lshlrev_b32_e32 v30, 16, v31
	v_and_b32_e32 v31, 0xffff0000, v31
	v_lshlrev_b32_e32 v68, 16, v32
	v_and_b32_e32 v69, 0xffff0000, v32
	v_lshlrev_b32_e32 v32, 16, v33
	v_and_b32_e32 v33, 0xffff0000, v33
	v_cvt_pk_bf16_f32 v5, v20, v21
	v_pk_fma_f32 v[18:19], v[58:59], s[38:39], v[46:47] op_sel_hi:[1,0,1]
	v_pk_fma_f32 v[6:7], v[22:23], s[38:39], v[6:7] op_sel_hi:[1,0,1]
	v_pk_fma_f32 v[20:21], v[60:61], s[38:39], v[48:49] op_sel_hi:[1,0,1]
	v_pk_fma_f32 v[8:9], v[24:25], s[38:39], v[8:9] op_sel_hi:[1,0,1]
	v_pk_fma_f32 v[22:23], v[62:63], s[38:39], v[50:51] op_sel_hi:[1,0,1]
	v_pk_fma_f32 v[10:11], v[26:27], s[38:39], v[10:11] op_sel_hi:[1,0,1]
	v_pk_fma_f32 v[24:25], v[64:65], s[38:39], v[52:53] op_sel_hi:[1,0,1]
	v_pk_fma_f32 v[12:13], v[28:29], s[38:39], v[12:13] op_sel_hi:[1,0,1]
	v_pk_fma_f32 v[26:27], v[66:67], s[38:39], v[54:55] op_sel_hi:[1,0,1]
	v_pk_fma_f32 v[14:15], v[30:31], s[38:39], v[14:15] op_sel_hi:[1,0,1]
	v_pk_fma_f32 v[28:29], v[68:69], s[38:39], v[56:57] op_sel_hi:[1,0,1]
	v_pk_fma_f32 v[16:17], v[32:33], s[38:39], v[16:17] op_sel_hi:[1,0,1]
	global_store_dwordx4 v[34:35], v[2:5], off
	s_nop 1
	v_cvt_pk_bf16_f32 v2, v18, v19
	v_cvt_pk_bf16_f32 v3, v6, v7
	v_cvt_pk_bf16_f32 v4, v20, v21
	v_cvt_pk_bf16_f32 v5, v8, v9
	v_cvt_pk_bf16_f32 v6, v22, v23
	v_cvt_pk_bf16_f32 v7, v10, v11
	v_cvt_pk_bf16_f32 v8, v24, v25
	v_cvt_pk_bf16_f32 v9, v12, v13
	v_cvt_pk_bf16_f32 v10, v26, v27
	v_cvt_pk_bf16_f32 v11, v14, v15
	v_cvt_pk_bf16_f32 v12, v28, v29
	v_cvt_pk_bf16_f32 v13, v16, v17
	global_store_dwordx4 v[36:37], v[2:5], off
	global_store_dwordx4 v[38:39], v[6:9], off
	global_store_dwordx4 v[40:41], v[10:13], off
	s_andn2_b64 vcc, exec, s[40:41]
	s_mov_b32 s34, s55
	s_mov_b32 s35, s51
	s_mov_b32 s22, s55
	s_mov_b32 s23, s51
	s_barrier
	s_cbranch_vccnz .LBB0_972
